# differential attention: V key rows loaded in a bit2/bit3-swapped order so the PV operand needs no permlane32_swap (8 fewer cross-lane swaps per tile)
# speedup vs baseline: 1.0041x; 1.0041x over previous
; __device__ __forceinline__ int v_st(int k, int c) { const int kk = (k & ~0xC) | ((k & 4) << 1) | ((k & 8) >> 1); return ((kk >> 3) * 4 + (c >> 5)) * 512 + ((kk & 7) * 32 + (c & 31)) * 2; }
; __device__ __forceinline__ int v_rd_base(int lane) { return ((lane & 3) << 3) | (((lane >> 2) & 3) << 6) | (((lane >> 4) & 1) << 5) | (((lane >> 5) & 1) << 8); }
; #define SLOAD(i, k0) do { sr_[i].vs0 = *reinterpret_cast<const bf16x8*>(&Vh[(long)((k0) + sr) * LDP + sc]); sr_[i].vs1 = *reinterpret_cast<const bf16x8*>(&Vh[(long)((k0) + 32 + sr) * LDP + sc]); \
;     sr_[i].ks0 = *reinterpret_cast<const bf16x8*>(&Kh[(long)((k0) + ksr) * LDP + ksc]); if (DK == 128) sr_[i].ks1 = *reinterpret_cast<const bf16x8*>(&Kh[(long)((k0) + 32 + ksr) * LDP + ksc]); } while (0)
; #define SWAIT() do { if (SD == 1) asm volatile("s_waitcnt vmcnt(0)" ::: "memory"); else if (DK == 128) asm volatile("s_waitcnt vmcnt(4)" ::: "memory"); else asm volatile("s_waitcnt vmcnt(3)" ::: "memory"); } while (0)
; #define HOOK(P0, P1, j) do { if (NA) na_hook(P0, P1, krow0 + (j), q_row, q_col, win_r, win_c, rpb, inv_scale, hi); } while (0)
; template <int DK, bool NA, bool QL, int SD> ...
;     ...
;   const bf16* Qw = Qb + (long)(wid * 32 + r32) * LDP + hi * 8;
; #pragma unroll
;   for (int d0 = 0; d0 < DK / 16; ++d0) { const bf16x8 qv = *reinterpret_cast<const bf16x8*>(Qw + d0 * 16); if (QL) *reinterpret_cast<bf16x8*>(ql + d0 * 1024) = qv; else qr[d0] = qv; }
;   const int sr = tid >> 4, sc = (tid & 15) * 8, vst0 = v_st(sr, sc), vst1 = v_st(32 + sr, sc);
;   const int ksr = DK == 128 ? sr : (tid >> 3), ksc = DK == 128 ? sc : (tid & 7) * 8;
;   const int vb0 = (int)(uintptr_t)V_lds + v_rd_base(lane);
;   struct { bf16x8 vs0, vs1, ks0, ks1; } sr_[SD];
;     ...
;   f32x16 pA0, pA1, pB0, pB1; float mnA, mnB, alA, alB; bf16x8 pa0, pa1, pa2, pa3;
;   constexpr int SE = 0, SO = SD - 1;
;   SLOAD(SE, 0); asm volatile("s_waitcnt vmcnt(0)" ::: "memory"); SWRITE(0, SE); __syncthreads();
;   qkt<DK, QL>(pA0, pA1, K_lds, qr, ql, r32, hi); HOOK(pA0, pA1, 0); partialSM(pA0, pA1, m_reg, mnA, alA, C, thrRaw);
;   SLOAD(SO, KVBLK); if (SD == 2) { if (2 < NT) SLOAD(SE, 2 * KVBLK); }
;   SWAIT(); SWRITE(1, SO); __syncthreads();
.LBB0_680:
	s_andn2_b64 vcc, exec, s[0:1]
	s_cbranch_vccnz .LBB0_369
	v_mov_b32_e32 v73, v188
	v_readlane_b32 s0, v253, 17
	v_readlane_b32 s1, v253, 18
	v_ashrrev_i32_e32 v74, 4, v73
	v_lshrrev_b32_e32 v162, 2, v74
	v_lshrrev_b32_e32 v155, 3, v74
	v_xor_b32_e32 v162, v162, v155
	v_and_b32_e32 v162, 1, v162
	v_mul_u32_u24_e32 v162, 12, v162
	v_xor_b32_e32 v155, v74, v162
	v_lshlrev_b32_e32 v16, 3, v73
	v_add_u32_e32 v18, 32, v74
	v_ashrrev_i32_e32 v75, 3, v73
	v_mov_b64_e32 v[50:51], s[0:1]
	s_movk_i32 s3, 0x2800
	v_and_b32_e32 v0, 0x78, v16
	v_mad_i64_i32 v[2:3], s[0:1], v155, s3, v[50:51]
	v_add_u32_e32 v162, 32, v155
	v_mad_i64_i32 v[4:5], s[0:1], v162, s3, v[50:51]
	v_mad_i64_i32 v[10:11], s[0:1], v75, s3, v[50:51]
	v_lshlrev_b32_e32 v52, 1, v0
	v_mov_b32_e32 v53, v1
	v_ashrrev_i32_e32 v0, 1, v73
	s_movk_i32 s0, 0xffe0
	v_lshlrev_b32_e32 v17, 4, v73
	v_lshl_add_u64 v[2:3], v[2:3], 0, v[52:53]
	v_lshl_add_u64 v[6:7], v[4:5], 0, v[52:53]
	v_bfi_b32 v0, s0, v0, v73
	v_readlane_b32 s0, v253, 9
	global_load_dwordx4 v[2:5], v[2:3], off offset:2048
	s_nop 0
	global_load_dwordx4 v[6:9], v[6:7], off offset:2048
	v_and_b32_e32 v54, 0x70, v17
	v_mov_b32_e32 v55, v1
	v_readlane_b32 s1, v253, 10
	v_lshl_add_u64 v[10:11], v[10:11], 0, v[54:55]
	global_load_dwordx4 v[10:13], v[10:11], off offset:1024
	v_mov_b64_e32 v[14:15], s[0:1]
	v_mad_i64_i32 v[14:15], s[0:1], v0, s3, v[14:15]
	v_lshrrev_b32_e32 v0, 1, v73
	v_and_b32_e32 v0, 16, v0
	v_lshl_add_u64 v[14:15], v[14:15], 0, v[0:1]
	global_load_dwordx4 v[110:113], v[14:15], off
	global_load_dwordx4 v[106:109], v[14:15], off offset:32
	global_load_dwordx4 v[98:101], v[14:15], off offset:64
	global_load_dwordx4 v[102:105], v[14:15], off offset:96
	v_add_u32_e32 v84, 64, v155
	v_add_u32_e32 v88, 0x60, v155
	v_add_u32_e32 v92, 64, v75
	v_mad_i64_i32 v[84:85], s[0:1], v84, s3, v[50:51]
	v_mad_i64_i32 v[88:89], s[0:1], v88, s3, v[50:51]
	v_mad_i64_i32 v[92:93], s[0:1], v92, s3, v[50:51]
	v_lshl_add_u64 v[84:85], v[84:85], 0, v[52:53]
	v_lshl_add_u64 v[88:89], v[88:89], 0, v[52:53]
	v_lshl_add_u64 v[92:93], v[92:93], 0, v[54:55]
	global_load_dwordx4 v[84:87], v[84:85], off offset:2048
	global_load_dwordx4 v[88:91], v[88:89], off offset:2048
	global_load_dwordx4 v[92:95], v[92:93], off offset:1024
	v_and_b32_e32 v20, 0xfffff0, v74
	v_lshlrev_b32_e32 v21, 1, v74
	v_lshrrev_b32_e32 v22, 1, v74
	v_and_b32_e32 v24, 3, v74
	v_and_or_b32 v20, v21, 8, v20
	v_and_or_b32 v21, v22, 4, v24
	v_and_b32_e32 v22, 0xfffff0, v18
	v_lshlrev_b32_e32 v18, 1, v18
	v_bfe_u32 v23, v16, 5, 2
	v_lshrrev_b32_e32 v14, 1, v20
	v_and_or_b32 v18, v18, 8, v22
	v_and_b32_e32 v76, 31, v73
	v_or_b32_e32 v14, v14, v23
	v_lshrrev_b32_e32 v18, 1, v18
	v_and_b32_e32 v25, 48, v17
	v_lshlrev_b32_e32 v60, 7, v76
	v_and_b32_e32 v16, 0x70, v16
	v_lshlrev_b32_e32 v15, 6, v21
	v_lshlrev_b32_e32 v14, 9, v14
	v_or_b32_e32 v18, v18, v23
	v_and_b32_e32 v19, 0x70, v73
	v_lshlrev_b32_e32 v26, 7, v75
	v_bitop3_b32 v24, v0, v60, v16 bitop3:0xde
	v_or3_b32 v14, v14, v15, v25
	v_lshlrev_b32_e32 v18, 9, v18
	v_bitop3_b32 v19, v54, v26, v19 bitop3:0xde
	v_add_u32_e32 v212, 0, v24
	v_or3_b32 v15, v18, v15, v25
	v_add_u32_e32 v214, 0, v14
	v_add_u32_e32 v213, 0, v19
	s_waitcnt vmcnt(0)
	v_add_u32_e32 v215, 0, v15
	s_add_i32 s8, 0, 0x10000
	v_and_b32_e32 v77, 63, v73
	v_add_u32_e32 v68, 64, v75
	v_mad_i64_i32 v[58:59], s[0:1], v155, s3, 0
	v_mad_i64_i32 v[56:57], s[0:1], v75, s3, 0
	v_mad_i64_i32 v[68:69], s[0:1], v68, s3, v[50:51]
	s_cmp_lg_u32 0, -1
	s_cselect_b32 s2, 0, 0
	v_lshl_add_u64 v[68:69], v[68:69], 0, v[54:55]
	s_waitcnt vmcnt(6)
	ds_write_b128 v214, v[2:5]
	s_waitcnt vmcnt(5)
	ds_write_b128 v215, v[6:9]
	s_waitcnt vmcnt(4)
	ds_write_b128 v213, v[10:13] offset:32768
	s_waitcnt lgkmcnt(0)
	s_barrier
	ds_read_b128 v[2:5], v212 offset:32768
	ds_read_b128 v[6:9], v212 offset:36864
	s_waitcnt vmcnt(3) lgkmcnt(1)
	v_mfma_f32_32x32x16_bf16 v[18:33], v[2:5], v[110:113], 0
	v_or_b32_e32 v2, 32, v0
	v_bitop3_b32 v2, v2, v60, v16 bitop3:0xde
	v_add_u32_e32 v216, 0, v2
	ds_read_b128 v[2:5], v216 offset:32768
	v_lshlrev_b32_e32 v10, 1, v73
	v_lshlrev_b32_e32 v11, 3, v77
	v_and_b32_e32 v12, 0xc0, v17
	s_waitcnt lgkmcnt(1)
	v_mfma_f32_32x32x16_bf16 v[34:49], v[6:9], v[110:113], 0
	v_and_b32_e32 v6, 0x3fffffc0, v73
	v_lshl_add_u32 v207, v6, 2, s8
	ds_read_b128 v[6:9], v216 offset:36864
	v_and_b32_e32 v10, 32, v10
	v_readlane_b32 s16, v254, 62
	v_readlane_b32 s17, v254, 63
	v_readlane_b32 s18, v255, 0
	s_waitcnt vmcnt(2) lgkmcnt(1)
	v_mfma_f32_32x32x16_bf16 v[18:33], v[2:5], v[106:109], v[18:33]
	v_or_b32_e32 v2, 64, v0
	v_bitop3_b32 v2, v2, v60, v16 bitop3:0xde
	v_add_u32_e32 v217, 0, v2
	ds_read_b128 v[2:5], v217 offset:32768
	v_readlane_b32 s19, v255, 1
	v_readlane_b32 s20, v255, 2
	v_readlane_b32 s21, v255, 3
	s_waitcnt lgkmcnt(1)
	v_mfma_f32_32x32x16_bf16 v[34:49], v[6:9], v[106:109], v[34:49]
	v_and_or_b32 v6, v11, 24, v12
	v_and_b32_e32 v7, 0x100, v11
	v_or3_b32 v78, v6, v10, v7
	ds_read_b128 v[6:9], v217 offset:36864
	v_readlane_b32 s22, v255, 4
	v_readlane_b32 s23, v255, 5
	v_readlane_b32 s24, v255, 6
	s_waitcnt vmcnt(1) lgkmcnt(1)
	v_mfma_f32_32x32x16_bf16 v[18:33], v[2:5], v[98:101], v[18:33]
	v_or_b32_e32 v2, 0x60, v0
	v_bitop3_b32 v2, v2, v60, v16 bitop3:0xde
	v_add_u32_e32 v218, 0, v2
	ds_read_b128 v[2:5], v218 offset:32768
	ds_read_b128 v[60:63], v218 offset:36864
	v_readlane_b32 s25, v255, 7
	v_readlane_b32 s26, v255, 8
	s_waitcnt lgkmcnt(2)
	v_mfma_f32_32x32x16_bf16 v[34:49], v[6:9], v[98:101], v[34:49]
	v_readlane_b32 s27, v255, 9
	v_readlane_b32 s28, v255, 10
	v_readlane_b32 s29, v255, 11
	v_readlane_b32 s30, v255, 12
	v_readlane_b32 s31, v255, 13
	s_mov_b32 s16, s17
	v_add_u32_e32 v211, s2, v78
	s_waitcnt vmcnt(0) lgkmcnt(1)
; #define SLOAD(i, k0) do { sr_[i].vs0 = *reinterpret_cast<const bf16x8*>(&Vh[(long)((k0) + sr) * LDP + sc]); sr_[i].vs1 = *reinterpret_cast<const bf16x8*>(&Vh[(long)((k0) + 32 + sr) * LDP + sc]); \
;     sr_[i].ks0 = *reinterpret_cast<const bf16x8*>(&Kh[(long)((k0) + ksr) * LDP + ksc]); if (DK == 128) sr_[i].ks1 = *reinterpret_cast<const bf16x8*>(&Kh[(long)((k0) + 32 + ksr) * LDP + ksc]); } while (0)
; #define SWAIT() do { if (SD == 1) asm volatile("s_waitcnt vmcnt(0)" ::: "memory"); else if (DK == 128) asm volatile("s_waitcnt vmcnt(4)" ::: "memory"); else asm volatile("s_waitcnt vmcnt(3)" ::: "memory"); } while (0)
; #define HOOK(P0, P1, j) do { if (NA) na_hook(P0, P1, krow0 + (j), q_row, q_col, win_r, win_c, rpb, inv_scale, hi); } while (0)
; __device__ __forceinline__ void partialSM(f32x16& p0, f32x16& p1, float& m_reg, float& mn, float& alpha, float C, float thrRaw) {
;   float pmax = p0[0];
; #pragma unroll
;   for (int r = 1; r < 16; ++r) pmax = fmaxf(pmax, p0[r]);
; #pragma unroll
;   for (int r = 0; r < 16; ++r) pmax = fmaxf(pmax, p1[r]);
;   { auto rr = __builtin_amdgcn_permlane32_swap(__float_as_uint(pmax), __float_as_uint(pmax), false, false);
;     pmax = fmaxf(__uint_as_float(rr[0]), __uint_as_float(rr[1])); }
;   if (__builtin_expect(__all(pmax - m_reg <= thrRaw), 1)) { mn = m_reg; alpha = 1.f; }
;   else { mn = fmaxf(m_reg, pmax); alpha = __builtin_amdgcn_exp2f((m_reg - mn) * C); m_reg = mn; }
;   float mnC = -mn * C;
; #pragma unroll
;   for (int r = 0; r < 16; ++r) p0[r] = fmaf(p0[r], C, mnC);
; #pragma unroll
;   for (int r = 0; r < 16; ++r) p1[r] = fmaf(p1[r], C, mnC);
; #pragma unroll
;   for (int r = 0; r < 16; ++r) p0[r] = __builtin_amdgcn_exp2f(p0[r]);
; }
; template <int DK, bool NA, bool QL, int SD> ...
;     ...
;   SLOAD(SE, 0); asm volatile("s_waitcnt vmcnt(0)" ::: "memory"); SWRITE(0, SE); __syncthreads();
;   qkt<DK, QL>(pA0, pA1, K_lds, qr, ql, r32, hi); HOOK(pA0, pA1, 0); partialSM(pA0, pA1, m_reg, mnA, alA, C, thrRaw);
;   SLOAD(SO, KVBLK); if (SD == 2) { if (2 < NT) SLOAD(SE, 2 * KVBLK); }
;   SWAIT(); SWRITE(1, SO); __syncthreads();
;   for (int j = 1; j + 1 < NT; j += 2) {
	v_mfma_f32_32x32x16_bf16 v[18:33], v[2:5], v[102:105], v[18:33]
	s_mov_b32 s18, s17
	s_mov_b32 s19, s17
	s_mov_b32 s20, s17
	s_mov_b32 s21, s17
	s_mov_b32 s22, s17
	s_mov_b32 s23, s17
	s_mov_b32 s24, s17
	s_waitcnt lgkmcnt(0)
	v_mfma_f32_32x32x16_bf16 v[34:49], v[60:63], v[102:105], v[34:49]
	s_nop 2
	v_max_f32_e32 v60, v19, v19
	v_max_f32_e32 v61, v18, v18
	v_max_f32_e32 v60, v61, v60
	v_max3_f32 v60, v60, v20, v21
	v_max3_f32 v60, v60, v22, v23
	v_max3_f32 v60, v60, v24, v25
	v_max3_f32 v60, v60, v26, v27
	v_max3_f32 v60, v60, v28, v29
	v_max3_f32 v60, v60, v30, v31
	v_max3_f32 v60, v60, v32, v33
	v_max3_f32 v60, v60, v34, v35
	v_max3_f32 v60, v60, v36, v37
	v_max3_f32 v60, v60, v38, v39
	v_max3_f32 v60, v60, v40, v41
	v_max3_f32 v72, v60, v42, v43
	v_max3_f32 v72, v72, v44, v45
	v_max3_f32 v72, v72, v46, v47
	v_max3_f32 v72, v72, v48, v49
	v_mov_b32_e32 v79, v72
	s_nop 1
	v_permlane32_swap_b32_e32 v72, v79
	v_add_u32_e32 v60, 64, v74
	v_add_u32_e32 v62, 0x60, v74
	v_max_f32_e32 v79, v79, v79
	v_max_f32_e32 v72, v72, v72
	v_mad_i64_i32 v[60:61], s[0:1], v60, s3, v[50:51]
	v_mad_i64_i32 v[62:63], s[0:1], v62, s3, v[50:51]
	v_max_f32_e32 v72, v72, v79
	v_add_f32_e32 v79, 0x7149f2ca, v72
	s_mov_b32 s0, 0x42800000
	v_max_f32_e32 v72, 0xf149f2ca, v72
	v_cmp_ge_f32_e32 vcc, s0, v79
	v_sub_f32_e32 v79, 0xf149f2ca, v72
	v_mul_f32_e32 v79, 0x3e38aa3b, v79
	v_exp_f32_e32 v79, v79
	s_cmp_eq_u64 vcc, exec
	s_cselect_b64 vcc, -1, 0
	v_cndmask_b32_e32 v142, v72, v199, vcc
	v_mul_f32_e32 v72, 0xbe38aa3b, v142
	v_cndmask_b32_e64 v219, v79, 1.0, vcc
	v_fmamk_f32 v79, v18, 0x3e38aa3b, v72
	v_add_u32_e32 v18, 0x80, v75
	v_fmamk_f32 v80, v19, 0x3e38aa3b, v72
	v_mad_i64_i32 v[18:19], s[0:1], v18, s3, v[50:51]
	v_lshl_add_u64 v[60:61], v[60:61], 0, v[52:53]
	v_lshl_add_u64 v[64:65], v[62:63], 0, v[52:53]
	v_lshl_add_u64 v[18:19], v[18:19], 0, v[54:55]
	s_nop 0
	v_fmamk_f32 v81, v20, 0x3e38aa3b, v72
	v_add_u32_e32 v20, 0x80, v155
	global_load_dwordx4 v[122:125], v[18:19], off offset:1024
	v_add_u32_e32 v18, 0xa0, v155
	v_mad_i64_i32 v[18:19], s[0:1], v18, s3, v[50:51]
	v_fmamk_f32 v82, v21, 0x3e38aa3b, v72
	v_lshl_add_u64 v[18:19], v[18:19], 0, v[52:53]
	v_mad_i64_i32 v[20:21], s[0:1], v20, s3, v[50:51]
	v_lshl_add_u64 v[20:21], v[20:21], 0, v[52:53]
	global_load_dwordx4 v[118:121], v[18:19], off offset:2048
	global_load_dwordx4 v[114:117], v[20:21], off offset:2048
	v_mov_b32_e32 v20, v72
	v_fmamk_f32 v22, v22, 0x3e38aa3b, v72
	v_fmamk_f32 v23, v23, 0x3e38aa3b, v72
	v_fmamk_f32 v24, v24, 0x3e38aa3b, v72
	v_fmamk_f32 v25, v25, 0x3e38aa3b, v72
	v_fmamk_f32 v26, v26, 0x3e38aa3b, v72
	v_fmamk_f32 v27, v27, 0x3e38aa3b, v72
	v_fmamk_f32 v28, v28, 0x3e38aa3b, v72
	v_fmamk_f32 v29, v29, 0x3e38aa3b, v72
	v_fmamk_f32 v30, v30, 0x3e38aa3b, v72
	v_fmamk_f32 v18, v31, 0x3e38aa3b, v72
	v_fmamk_f32 v19, v32, 0x3e38aa3b, v72
	v_fmac_f32_e32 v20, 0x3e38aa3b, v33
	s_mov_b32 s25, s17
	s_mov_b32 s26, s17
	s_mov_b32 s27, s17
	s_mov_b32 s28, s17
	s_mov_b32 s29, s17
	s_mov_b32 s30, s17
	s_mov_b32 s31, s17
	v_mov_b64_e32 v[2:3], s[16:17]
	v_exp_f32_e32 v177, v79
	v_exp_f32_e32 v226, v80
	v_exp_f32_e32 v161, v81
	v_exp_f32_e32 v223, v82
	v_exp_f32_e32 v153, v22
	v_exp_f32_e32 v176, v23
	v_exp_f32_e32 v152, v24
	v_exp_f32_e32 v160, v25
	v_exp_f32_e32 v149, v26
	v_exp_f32_e32 v151, v27
	v_exp_f32_e32 v147, v28
	v_exp_f32_e32 v150, v29
	v_exp_f32_e32 v145, v30
	v_exp_f32_e32 v148, v18
	v_exp_f32_e32 v144, v19
	v_exp_f32_e32 v146, v20
	s_addk_i32 s2, 0x4000
	v_and_b32_e32 v18, 15, v73
	v_mov_b64_e32 v[16:17], s[30:31]
	s_waitcnt vmcnt(3)
	v_add_u32_e32 v210, s2, v78
	v_lshl_or_b32 v58, v18, 4, v58
	v_readlane_b32 s2, v254, 34
	v_and_b32_e32 v18, 7, v73
	v_mov_b64_e32 v[4:5], s[18:19]
	v_mov_b64_e32 v[6:7], s[20:21]
	v_mov_b64_e32 v[8:9], s[22:23]
	v_mov_b64_e32 v[10:11], s[24:25]
	v_mov_b64_e32 v[12:13], s[26:27]
	v_mov_b64_e32 v[14:15], s[28:29]
	s_mov_b32 s0, 0x3e38aa3b
	v_readlane_b32 s3, v254, 35
	v_lshl_or_b32 v56, v18, 4, v56
	v_mov_b32_e32 v209, 0
	v_mov_b64_e32 v[32:33], v[16:17]
	s_mov_b32 s9, 1
	s_mov_b32 s13, s17
	v_pk_fma_f32 v[132:133], v[48:49], s[0:1], v[72:73] op_sel_hi:[1,0,0]
	v_pk_fma_f32 v[134:135], v[46:47], s[0:1], v[72:73] op_sel_hi:[1,0,0]
	v_pk_fma_f32 v[140:141], v[44:45], s[0:1], v[72:73] op_sel_hi:[1,0,0]
	v_pk_fma_f32 v[126:127], v[42:43], s[0:1], v[72:73] op_sel_hi:[1,0,0]
	v_pk_fma_f32 v[128:129], v[40:41], s[0:1], v[72:73] op_sel_hi:[1,0,0]
	v_pk_fma_f32 v[130:131], v[38:39], s[0:1], v[72:73] op_sel_hi:[1,0,0]
	v_pk_fma_f32 v[136:137], v[36:37], s[0:1], v[72:73] op_sel_hi:[1,0,0]
	v_pk_fma_f32 v[138:139], v[34:35], s[0:1], v[72:73] op_sel_hi:[1,0,0]
	s_waitcnt vmcnt(5)
	ds_write_b128 v214, v[84:87] offset:16384
	s_waitcnt vmcnt(4)
	ds_write_b128 v215, v[88:91] offset:16384
	s_waitcnt vmcnt(3)
	ds_write_b128 v213, v[92:95] offset:49152
	v_cmp_gt_u32_e64 s[0:1], 32, v77
	v_lshl_add_u32 v208, v76, 2, v207
	v_lshl_add_u64 v[156:157], s[2:3], 0, v[58:59]
	v_lshl_add_u64 v[158:159], s[2:3], 0, v[56:57]
	v_mov_b64_e32 v[30:31], v[14:15]
	v_mov_b64_e32 v[28:29], v[12:13]
	v_mov_b64_e32 v[26:27], v[10:11]
	v_mov_b64_e32 v[24:25], v[8:9]
	v_mov_b64_e32 v[22:23], v[6:7]
	v_mov_b64_e32 v[20:21], v[4:5]
	v_mov_b64_e32 v[18:19], v[2:3]
	v_mov_b32_e32 v34, 0
	v_mov_b32_e32 v35, v209
	v_mov_b32_e32 v36, v209
	v_mov_b32_e32 v37, v209
	v_mov_b32_e32 v38, v209
	v_mov_b32_e32 v39, v209
	v_mov_b32_e32 v40, v209
	v_mov_b32_e32 v41, v209
	v_mov_b32_e32 v42, v209
	v_mov_b32_e32 v43, v209
	v_mov_b32_e32 v44, v209
	v_mov_b32_e32 v45, v209
	v_mov_b32_e32 v46, v209
	v_mov_b32_e32 v47, v209
	v_mov_b32_e32 v48, v209
	v_mov_b32_e32 v49, v209
	v_mov_b32_e32 v50, 0
	v_mov_b32_e32 v51, v209
	v_mov_b32_e32 v52, v209
	v_mov_b32_e32 v53, v209
	v_mov_b32_e32 v54, v209
	v_mov_b32_e32 v55, v209
	v_mov_b32_e32 v56, v209
	v_mov_b32_e32 v57, v209
	v_mov_b32_e32 v58, v209
	v_mov_b32_e32 v59, v209
	v_mov_b32_e32 v60, v209
	v_mov_b32_e32 v61, v209
	v_mov_b32_e32 v62, v209
	v_mov_b32_e32 v63, v209
	v_mov_b32_e32 v64, v209
	v_mov_b32_e32 v65, v209
	v_readlane_b32 s6, v254, 32
	v_readlane_b32 s7, v254, 33
	s_nop 3
	v_lshl_add_u64 v[178:179], v[156:157], 0, s[6:7]
	v_lshl_add_u64 v[204:205], v[158:159], 0, s[6:7]
	s_mov_b32 s6, 0xe130000
	s_mov_b32 s7, 0
	s_nop 0
	v_lshl_add_u64 v[180:181], v[178:179], 0, s[6:7]
	s_mov_b32 s6, 0xe0e0000
	s_nop 0
	v_lshl_add_u64 v[178:179], v[178:179], 0, s[6:7]
	v_lshl_add_u64 v[204:205], v[204:205], 0, s[6:7]
	s_waitcnt lgkmcnt(0)
	s_barrier
; __device__ __forceinline__ void finishSM(f32x16& p0, f32x16& p1, float alpha, float& l_reg, bf16x8& pa0, bf16x8& pa1, bf16x8& pa2, bf16x8& pa3) {
; #pragma unroll
;   for (int r = 0; r < 16; ++r) p1[r] = __builtin_amdgcn_exp2f(p1[r]);
;   float ps = 0;
; #pragma unroll
;   for (int r = 0; r < 16; ++r) ps += p0[r];
; #pragma unroll
;   for (int r = 0; r < 16; ++r) ps += p1[r];
;   { auto rr = __builtin_amdgcn_permlane32_swap(__float_as_uint(ps), __float_as_uint(ps), false, false);
;     ps = __uint_as_float(rr[0]) + __uint_as_float(rr[1]); }
;   l_reg = l_reg * alpha + ps;
;     ...
;   PK4(p0, 0, pa0); PK4(p0, 8, pa1); PK4(p1, 0, pa2); PK4(p1, 8, pa3);
;     ...
; }
; template <int DK, bool QL>
; __device__ __forceinline__ void qkt(f32x16& p0, f32x16& p1, const bf16* Ks, const bf16x8* qr, const char* ql, int r32, int hi) {
;   p0 = f32x16{}; p1 = f32x16{};
; #pragma unroll
;   for (int d0 = 0; d0 < DK / 16; ++d0) { int cb = (d0 * 16 + hi * 8) * 2;
;     const bf16x8 qv = QL ? *reinterpret_cast<const bf16x8*>(ql + d0 * 1024) : qr[d0];
;     bf16x8 b0 = *reinterpret_cast<const bf16x8*>((const char*)Ks + kswz<DK>(r32, cb));
;     bf16x8 b1 = *reinterpret_cast<const bf16x8*>((const char*)Ks + kswz<DK>(32 + r32, cb));
;     p0 = __builtin_amdgcn_mfma_f32_32x32x16_bf16(b0, qv, p0, 0, 0, 0);
;     p1 = __builtin_amdgcn_mfma_f32_32x32x16_bf16(b1, qv, p1, 0, 0, 0); }
; }
; __device__ __forceinline__ void na_hook(f32x16& p0, f32x16& p1, int kr, int q_row, int q_col, int win_r, int win_c, const float* rpb, float inv_scale, int hi) {
;   const bool rowok = (kr >= win_r) && (kr < win_r + 8);
;   int ir = kr - q_row + 7; ir = ir < 0 ? 0 : (ir > 14 ? 14 : ir);
;   const float* rp = rpb + ir * 31;
; #pragma unroll
;   for (int r = 0; r < 16; ++r) {
;     const int kc = crow(r, hi);
;     { const bool ok = rowok && kc >= win_c && kc < win_c + 16; int ic = kc - q_col + 15; ic = ic < 0 ? 0 : (ic > 30 ? 30 : ic);
;       p0[r] = ok ? fmaf(rp[ic], inv_scale, p0[r]) : -1e30f; }
;     { const int kc2 = kc + 32; const bool ok = rowok && kc2 >= win_c && kc2 < win_c + 16; int ic = kc2 - q_col + 15; ic = ic < 0 ? 0 : (ic > 30 ? 30 : ic);
;       p1[r] = ok ? fmaf(rp[ic], inv_scale, p1[r]) : -1e30f; }
;   }
; }
; __device__ __forceinline__ int v_st(int k, int c) { const int kk = (k & ~0xC) | ((k & 4) << 1) | ((k & 8) >> 1); return ((kk >> 3) * 4 + (c >> 5)) * 512 + ((kk & 7) * 32 + (c & 31)) * 2; }
.LBB0_682:
	ds_read_b128 v[66:69], v212 offset:49152
	ds_read_b128 v[70:73], v212 offset:53248
	v_exp_f32_e32 v143, v138
	v_add_f32_e32 v138, v226, v177
	s_waitcnt lgkmcnt(1)
	v_mfma_f32_32x32x16_bf16 v[82:97], v[66:69], v[110:113], 0
	v_add_f32_e32 v138, v161, v138
	v_add_f32_e32 v138, v223, v138
	v_add_f32_e32 v138, v153, v138
	ds_read_b128 v[228:231], v216 offset:49152
	ds_read_b128 v[232:235], v216 offset:53248
	v_add_f32_e32 v138, v176, v138
	v_add_f32_e32 v138, v152, v138
	v_add_f32_e32 v138, v160, v138
	s_waitcnt lgkmcnt(2)
	v_mfma_f32_32x32x16_bf16 v[66:81], v[70:73], v[110:113], 0
	v_add_f32_e32 v138, v149, v138
	v_add_f32_e32 v138, v151, v138
	v_add_f32_e32 v138, v147, v138
	v_add_f32_e32 v138, v150, v138
	v_add_f32_e32 v138, v145, v138
	v_exp_f32_e32 v164, v139
	v_add_f32_e32 v138, v148, v138
	s_waitcnt lgkmcnt(1)
	v_mfma_f32_32x32x16_bf16 v[82:97], v[228:231], v[106:109], v[82:97]
	v_exp_f32_e32 v136, v136
	v_add_f32_e32 v138, v144, v138
	v_exp_f32_e32 v137, v137
	v_add_f32_e32 v138, v146, v138
	v_exp_f32_e32 v130, v130
	v_add_f32_e32 v138, v143, v138
	v_exp_f32_e32 v131, v131
	s_waitcnt lgkmcnt(0)
	v_mfma_f32_32x32x16_bf16 v[66:81], v[232:235], v[106:109], v[66:81]
	ds_read_b128 v[228:231], v217 offset:49152
	ds_read_b128 v[232:235], v217 offset:53248
	v_add_f32_e32 v138, v164, v138
	v_exp_f32_e32 v128, v128
	v_add_f32_e32 v138, v136, v138
	v_exp_f32_e32 v129, v129
	v_add_f32_e32 v138, v137, v138
	v_exp_f32_e32 v126, v126
	s_waitcnt lgkmcnt(1)
	v_mfma_f32_32x32x16_bf16 v[82:97], v[228:231], v[98:101], v[82:97]
	v_add_f32_e32 v138, v130, v138
	v_exp_f32_e32 v127, v127
	v_add_f32_e32 v138, v131, v138
	v_exp_f32_e32 v165, v140
	v_add_f32_e32 v138, v128, v138
	v_exp_f32_e32 v166, v141
	v_add_f32_e32 v138, v129, v138
	s_waitcnt lgkmcnt(0)
	v_mfma_f32_32x32x16_bf16 v[66:81], v[232:235], v[98:101], v[66:81]
	ds_read_b128 v[228:231], v218 offset:49152
	ds_read_b128 v[232:235], v218 offset:53248
	v_exp_f32_e32 v134, v134
	v_add_f32_e32 v138, v126, v138
	v_exp_f32_e32 v135, v135
	v_add_f32_e32 v138, v127, v138
	v_exp_f32_e32 v132, v132
	v_add_f32_e32 v138, v165, v138
	s_waitcnt lgkmcnt(1)
	v_mfma_f32_32x32x16_bf16 v[82:97], v[228:231], v[102:105], v[82:97]
	v_exp_f32_e32 v133, v133
	v_add_f32_e32 v138, v166, v138
	v_add_f32_e32 v138, v134, v138
	v_add_f32_e32 v138, v135, v138
	v_add_f32_e32 v138, v132, v138
	v_add_f32_e32 v220, v133, v138
	v_mov_b32_e32 v221, v220
	s_waitcnt lgkmcnt(0)
	v_mfma_f32_32x32x16_bf16 v[66:81], v[232:235], v[102:105], v[66:81]
	v_cvt_pk_bf16_f32 v138, v177, v226
	v_cvt_pk_bf16_f32 v139, v161, v223
	v_cvt_pk_bf16_f32 v140, v153, v176
	v_cvt_pk_bf16_f32 v141, v152, v160
	v_cvt_pk_bf16_f32 v222, v149, v151
	v_cvt_pk_bf16_f32 v223, v147, v150
	v_cvt_pk_bf16_f32 v224, v145, v148
	v_permlane32_swap_b32_e32 v220, v221
	v_cvt_pk_bf16_f32 v225, v144, v146
	v_cvt_pk_bf16_f32 v144, v143, v164
	v_cvt_pk_bf16_f32 v145, v136, v137
	v_cvt_pk_bf16_f32 v146, v130, v131
	v_cvt_pk_bf16_f32 v147, v128, v129
	v_cvt_pk_bf16_f32 v148, v126, v127
	v_cvt_pk_bf16_f32 v149, v165, v166
	v_cvt_pk_bf16_f32 v150, v134, v135
	v_cvt_pk_bf16_f32 v151, v132, v133
	global_load_dwordx4 v[182:185], v[178:179], off offset:2048
	global_load_dwordx4 v[194:197], v[180:181], off offset:2048
	global_load_dwordx4 v[134:137], v[204:205], off offset:1024
	s_mov_b32 s4, 0xa0000
	s_mov_b32 s5, 0
	s_nop 0
	v_lshl_add_u64 v[178:179], v[178:179], 0, s[4:5]
	v_lshl_add_u64 v[180:181], v[180:181], 0, s[4:5]
	v_lshl_add_u64 v[204:205], v[204:205], 0, s[4:5]
	ds_read_b64_tr_b16 v[226:227], v211 offset:0
	ds_read_b64_tr_b16 v[228:229], v211 offset:0x800
	ds_read_b64_tr_b16 v[230:231], v211 offset:0x1000
	ds_read_b64_tr_b16 v[232:233], v211 offset:0x1800
	ds_read_b64_tr_b16 v[234:235], v211 offset:0x2000
	ds_read_b64_tr_b16 v[236:237], v211 offset:0x2800
	ds_read_b64_tr_b16 v[238:239], v211 offset:0x3000
	ds_read_b64_tr_b16 v[240:241], v211 offset:0x3800
	s_waitcnt lgkmcnt(4)
	s_nop 0
	v_mfma_f32_32x32x16_bf16 v[18:33], v[138:141], v[226:229], v[18:33]
	ds_read_b64_tr_b16 v[226:227], v211 offset:0x200
	ds_read_b64_tr_b16 v[228:229], v211 offset:0xa00
	v_mfma_f32_32x32x16_bf16 v[18:33], v[222:225], v[230:233], v[18:33]
	ds_read_b64_tr_b16 v[230:231], v211 offset:0x1200
	ds_read_b64_tr_b16 v[232:233], v211 offset:0x1a00
	s_waitcnt lgkmcnt(4)
	v_mfma_f32_32x32x16_bf16 v[18:33], v[144:147], v[234:237], v[18:33]
	ds_read_b64_tr_b16 v[234:235], v211 offset:0x2200
	ds_read_b64_tr_b16 v[236:237], v211 offset:0x2a00
	v_mfma_f32_32x32x16_bf16 v[18:33], v[148:151], v[238:241], v[18:33]
	ds_read_b64_tr_b16 v[238:239], v211 offset:0x3200
	ds_read_b64_tr_b16 v[240:241], v211 offset:0x3a00
	s_waitcnt lgkmcnt(4)
	v_mfma_f32_32x32x16_bf16 v[2:17], v[138:141], v[226:229], v[2:17]
	ds_read_b64_tr_b16 v[226:227], v211 offset:0x400
	ds_read_b64_tr_b16 v[228:229], v211 offset:0xc00
	v_mfma_f32_32x32x16_bf16 v[2:17], v[222:225], v[230:233], v[2:17]
	ds_read_b64_tr_b16 v[230:231], v211 offset:0x1400
	ds_read_b64_tr_b16 v[232:233], v211 offset:0x1c00
	s_waitcnt lgkmcnt(4)
	v_mfma_f32_32x32x16_bf16 v[2:17], v[144:147], v[234:237], v[2:17]
	ds_read_b64_tr_b16 v[234:235], v211 offset:0x2400
	ds_read_b64_tr_b16 v[236:237], v211 offset:0x2c00
	v_mfma_f32_32x32x16_bf16 v[2:17], v[148:151], v[238:241], v[2:17]
	ds_read_b64_tr_b16 v[238:239], v211 offset:0x3400
	ds_read_b64_tr_b16 v[240:241], v211 offset:0x3c00
	s_waitcnt lgkmcnt(4)
	v_mfma_f32_32x32x16_bf16 v[50:65], v[138:141], v[226:229], v[50:65]
	ds_read_b64_tr_b16 v[226:227], v211 offset:0x600
	ds_read_b64_tr_b16 v[228:229], v211 offset:0xe00
	v_mfma_f32_32x32x16_bf16 v[50:65], v[222:225], v[230:233], v[50:65]
	ds_read_b64_tr_b16 v[230:231], v211 offset:0x1600
	ds_read_b64_tr_b16 v[232:233], v211 offset:0x1e00
	s_waitcnt lgkmcnt(4)
; #define SBAR() __builtin_amdgcn_sched_barrier(0)
; #define SLOAD(i, k0) do { sr_[i].vs0 = *reinterpret_cast<const bf16x8*>(&Vh[(long)((k0) + sr) * LDP + sc]); sr_[i].vs1 = *reinterpret_cast<const bf16x8*>(&Vh[(long)((k0) + 32 + sr) * LDP + sc]); \
;     sr_[i].ks0 = *reinterpret_cast<const bf16x8*>(&Kh[(long)((k0) + ksr) * LDP + ksc]); if (DK == 128) sr_[i].ks1 = *reinterpret_cast<const bf16x8*>(&Kh[(long)((k0) + 32 + ksr) * LDP + ksc]); } while (0)
; __device__ __forceinline__ void partialSM(f32x16& p0, f32x16& p1, float& m_reg, float& mn, float& alpha, float C, float thrRaw) {
;   float pmax = p0[0];
; #pragma unroll
;   for (int r = 1; r < 16; ++r) pmax = fmaxf(pmax, p0[r]);
; #pragma unroll
;   for (int r = 0; r < 16; ++r) pmax = fmaxf(pmax, p1[r]);
;   { auto rr = __builtin_amdgcn_permlane32_swap(__float_as_uint(pmax), __float_as_uint(pmax), false, false);
;     pmax = fmaxf(__uint_as_float(rr[0]), __uint_as_float(rr[1])); }
;   if (__builtin_expect(__all(pmax - m_reg <= thrRaw), 1)) { mn = m_reg; alpha = 1.f; }
;   else { mn = fmaxf(m_reg, pmax); alpha = __builtin_amdgcn_exp2f((m_reg - mn) * C); m_reg = mn; }
;   float mnC = -mn * C;
; #pragma unroll
;   for (int r = 0; r < 16; ++r) p0[r] = fmaf(p0[r], C, mnC);
; #pragma unroll
;   for (int r = 0; r < 16; ++r) p1[r] = fmaf(p1[r], C, mnC);
; #pragma unroll
;   for (int r = 0; r < 16; ++r) p0[r] = __builtin_amdgcn_exp2f(p0[r]);
; }
; template <int DK, bool NA, bool QL, int SD> ...
;     ...
;   f32x16 pA0, pA1, pB0, pB1; float mnA, mnB, alA, alB; bf16x8 pa0, pa1, pa2, pa3;
;   constexpr int SE = 0, SO = SD - 1;
;   SLOAD(SE, 0); asm volatile("s_waitcnt vmcnt(0)" ::: "memory"); SWRITE(0, SE); __syncthreads();
;   qkt<DK, QL>(pA0, pA1, K_lds, qr, ql, r32, hi); HOOK(pA0, pA1, 0); partialSM(pA0, pA1, m_reg, mnA, alA, C, thrRaw);
;   SLOAD(SO, KVBLK); if (SD == 2) { if (2 < NT) SLOAD(SE, 2 * KVBLK); }
;   SWAIT(); SWRITE(1, SO); __syncthreads();
;   for (int j = 1; j + 1 < NT; j += 2) {
;     SBAR(); qkt<DK, QL>(pB0, pB1, (bf16*)((char*)K_lds + SHM_K), qr, ql, r32, hi); HOOK(pB0, pB1, j);
;     finishSM(pA0, pA1, alA, l_reg, pa0, pa1, pa2, pa3); SBAR();
;     SLOAD(SO, (j + SD) * KVBLK); SBAR();
;     pv_d0(o, vb0, pa0, pa1, pa2, pa3); partialSM(pB0, pB1, m_reg, mnB, alB, C, thrRaw);
;     __syncthreads(); SWAIT(); SWRITE(0, SE);
;     RESC(alB); __syncthreads();
	v_mfma_f32_32x32x16_bf16 v[50:65], v[144:147], v[234:237], v[50:65]
	ds_read_b64_tr_b16 v[234:235], v211 offset:0x2600
	ds_read_b64_tr_b16 v[236:237], v211 offset:0x2e00
	v_mfma_f32_32x32x16_bf16 v[50:65], v[148:151], v[238:241], v[50:65]
	ds_read_b64_tr_b16 v[238:239], v211 offset:0x3600
	ds_read_b64_tr_b16 v[240:241], v211 offset:0x3e00
	s_waitcnt lgkmcnt(6)
	v_mfma_f32_32x32x16_bf16 v[34:49], v[138:141], v[226:229], v[34:49]
	v_max_f32_e32 v138, v83, v82
	v_max3_f32 v138, v138, v84, v85
	v_max3_f32 v138, v138, v86, v87
	v_max3_f32 v138, v138, v88, v89
	v_max3_f32 v138, v138, v90, v91
	v_max3_f32 v138, v138, v92, v93
	v_max3_f32 v138, v138, v94, v95
	s_waitcnt lgkmcnt(4)
	v_mfma_f32_32x32x16_bf16 v[34:49], v[222:225], v[230:233], v[34:49]
	v_max3_f32 v138, v138, v96, v97
	v_max3_f32 v138, v138, v66, v67
	v_max3_f32 v138, v138, v68, v69
	v_max3_f32 v138, v138, v70, v71
	v_max3_f32 v138, v138, v72, v73
	v_max3_f32 v138, v138, v74, v75
	v_max3_f32 v138, v138, v76, v77
	v_max3_f32 v138, v138, v78, v79
	s_waitcnt lgkmcnt(2)
	v_mfma_f32_32x32x16_bf16 v[34:49], v[144:147], v[234:237], v[34:49]
	v_max3_f32 v138, v138, v80, v81
	v_mov_b32_e32 v139, v138
	s_nop 1
	v_permlane32_swap_b32_e32 v138, v139
	v_max_f32_e32 v138, v139, v138
	v_sub_f32_e32 v139, v138, v142
	s_mov_b32 s2, 0x42800000
	v_cmp_ge_f32_e32 vcc, s2, v139
	v_max_f32_e32 v138, v142, v138
	s_waitcnt lgkmcnt(0)
	v_mfma_f32_32x32x16_bf16 v[34:49], v[148:151], v[238:241], v[34:49]
	v_sub_f32_e32 v139, v142, v138
	v_mul_f32_e32 v139, 0x3e38aa3b, v139
	v_exp_f32_e32 v139, v139
	s_cmp_eq_u64 vcc, exec
	s_cselect_b64 s[2:3], -1, 0
	s_waitcnt vmcnt(3)
	v_cndmask_b32_e64 v222, v139, 1.0, s[2:3]
	v_cmp_gt_f32_e32 vcc, 1.0, v222
	ds_write_b128 v213, v[122:125] offset:32768
	s_cbranch_vccz .LBB0_686
	s_and_saveexec_b64 s[4:5], s[0:1]
	ds_write_b32 v208, v222 offset:128
	s_or_b64 exec, exec, s[4:5]
	s_waitcnt lgkmcnt(0)
	v_add_u32_e32 v139, v207, v0
	ds_read_b128 v[144:147], v139 offset:128
	ds_read_b128 v[148:151], v139 offset:160
	ds_read_b128 v[224:227], v139 offset:192
	ds_read_b128 v[228:231], v139 offset:224
	s_waitcnt lgkmcnt(3)
	v_pk_mul_f32 v[2:3], v[144:145], v[2:3]
	v_pk_mul_f32 v[4:5], v[4:5], v[146:147]
	s_waitcnt lgkmcnt(2)
	v_pk_mul_f32 v[6:7], v[6:7], v[148:149]
	v_pk_mul_f32 v[8:9], v[8:9], v[150:151]
	s_waitcnt lgkmcnt(1)
	v_pk_mul_f32 v[10:11], v[10:11], v[224:225]
	v_pk_mul_f32 v[12:13], v[12:13], v[226:227]
	s_waitcnt lgkmcnt(0)
	v_pk_mul_f32 v[14:15], v[14:15], v[228:229]
	v_pk_mul_f32 v[30:31], v[30:31], v[228:229]
	v_pk_mul_f32 v[26:27], v[26:27], v[224:225]
	v_pk_mul_f32 v[22:23], v[22:23], v[148:149]
	v_pk_mul_f32 v[32:33], v[32:33], v[230:231]
	v_pk_mul_f32 v[28:29], v[28:29], v[226:227]
	v_pk_mul_f32 v[24:25], v[24:25], v[150:151]
	v_pk_mul_f32 v[20:21], v[20:21], v[146:147]
	v_pk_mul_f32 v[18:19], v[18:19], v[144:145]
	v_pk_mul_f32 v[16:17], v[16:17], v[230:231]
	v_pk_mul_f32 v[34:35], v[144:145], v[34:35]
	v_pk_mul_f32 v[36:37], v[36:37], v[146:147]
	v_pk_mul_f32 v[38:39], v[38:39], v[148:149]
	v_pk_mul_f32 v[40:41], v[40:41], v[150:151]
	v_pk_mul_f32 v[42:43], v[42:43], v[224:225]
	v_pk_mul_f32 v[44:45], v[44:45], v[226:227]
	v_pk_mul_f32 v[46:47], v[46:47], v[228:229]
	v_pk_mul_f32 v[62:63], v[62:63], v[228:229]
	v_pk_mul_f32 v[58:59], v[58:59], v[224:225]
	v_pk_mul_f32 v[54:55], v[54:55], v[148:149]
	v_pk_mul_f32 v[64:65], v[64:65], v[230:231]
	v_pk_mul_f32 v[60:61], v[60:61], v[226:227]
	v_pk_mul_f32 v[56:57], v[56:57], v[150:151]
	v_pk_mul_f32 v[52:53], v[52:53], v[146:147]
	v_pk_mul_f32 v[50:51], v[50:51], v[144:145]
	v_pk_mul_f32 v[48:49], v[48:49], v[230:231]
; #define SBAR() __builtin_amdgcn_sched_barrier(0)
; #define SLOAD(i, k0) do { sr_[i].vs0 = *reinterpret_cast<const bf16x8*>(&Vh[(long)((k0) + sr) * LDP + sc]); sr_[i].vs1 = *reinterpret_cast<const bf16x8*>(&Vh[(long)((k0) + 32 + sr) * LDP + sc]); \
;     sr_[i].ks0 = *reinterpret_cast<const bf16x8*>(&Kh[(long)((k0) + ksr) * LDP + ksc]); if (DK == 128) sr_[i].ks1 = *reinterpret_cast<const bf16x8*>(&Kh[(long)((k0) + 32 + ksr) * LDP + ksc]); } while (0)
; #define SWAIT() do { if (SD == 1) asm volatile("s_waitcnt vmcnt(0)" ::: "memory"); else if (DK == 128) asm volatile("s_waitcnt vmcnt(4)" ::: "memory"); else asm volatile("s_waitcnt vmcnt(3)" ::: "memory"); } while (0)
; #define RESC(a) do { if (__any((a) < 1.f)) { if (hi == 0) al_l[r32] = (a); asm volatile("s_waitcnt lgkmcnt(0)" ::: "memory"); \
;     _Pragma("unroll") for (int d = 0; d < 4; ++d) _Pragma("unroll") for (int r = 0; r < 16; ++r) o[d][r] *= al_l[crow(r, hi)]; } } while (0)
; #define HOOK(P0, P1, j) do { if (NA) na_hook(P0, P1, krow0 + (j), q_row, q_col, win_r, win_c, rpb, inv_scale, hi); } while (0)
; __device__ __forceinline__ void finishSM(f32x16& p0, f32x16& p1, float alpha, float& l_reg, bf16x8& pa0, bf16x8& pa1, bf16x8& pa2, bf16x8& pa3) {
; #pragma unroll
;   for (int r = 0; r < 16; ++r) p1[r] = __builtin_amdgcn_exp2f(p1[r]);
;   float ps = 0;
; #pragma unroll
;   for (int r = 0; r < 16; ++r) ps += p0[r];
; #pragma unroll
;   for (int r = 0; r < 16; ++r) ps += p1[r];
;   { auto rr = __builtin_amdgcn_permlane32_swap(__float_as_uint(ps), __float_as_uint(ps), false, false);
;     ps = __uint_as_float(rr[0]) + __uint_as_float(rr[1]); }
;   l_reg = l_reg * alpha + ps;
;     ...
;   PK4(p0, 0, pa0); PK4(p0, 8, pa1); PK4(p1, 0, pa2); PK4(p1, 8, pa3);
;     ...
; }
; template <int DK, bool NA, bool QL, int SD> ...
;     ...
;     __syncthreads(); SWAIT(); SWRITE(0, SE);
;     RESC(alB); __syncthreads();
;     SBAR(); qkt<DK, QL>(pA0, pA1, K_lds, qr, ql, r32, hi); HOOK(pA0, pA1, j + 1);
;     finishSM(pB0, pB1, alB, l_reg, pa0, pa1, pa2, pa3); SBAR();
;     if (SD == 1 || j + 3 < NT) SLOAD(SE, (j + 1 + SD) * KVBLK); SBAR();
;     pv_d0(o, vb0 + (int)SHM_V, pa0, pa1, pa2, pa3); partialSM(pA0, pA1, m_reg, mnA, alA, C, thrRaw);
.LBB0_686:
	v_cndmask_b32_e64 v223, v138, v142, s[2:3]
	v_mul_f32_e32 v224, 0xbe38aa3b, v223
	s_mov_b32 s2, 0x3e38aa3b
	v_pk_fma_f32 v[82:83], v[82:83], s[2:3], v[224:225] op_sel_hi:[1,0,0]
	v_pk_fma_f32 v[84:85], v[84:85], s[2:3], v[224:225] op_sel_hi:[1,0,0]
	v_pk_fma_f32 v[86:87], v[86:87], s[2:3], v[224:225] op_sel_hi:[1,0,0]
	v_pk_fma_f32 v[88:89], v[88:89], s[2:3], v[224:225] op_sel_hi:[1,0,0]
	v_pk_fma_f32 v[90:91], v[90:91], s[2:3], v[224:225] op_sel_hi:[1,0,0]
	v_pk_fma_f32 v[92:93], v[92:93], s[2:3], v[224:225] op_sel_hi:[1,0,0]
	v_pk_fma_f32 v[94:95], v[94:95], s[2:3], v[224:225] op_sel_hi:[1,0,0]
	v_pk_fma_f32 v[96:97], v[96:97], s[2:3], v[224:225] op_sel_hi:[1,0,0]
	v_exp_f32_e32 v138, v82
	v_exp_f32_e32 v153, v83
	v_exp_f32_e32 v139, v84
	v_exp_f32_e32 v152, v85
	v_exp_f32_e32 v140, v86
	v_exp_f32_e32 v151, v87
	v_exp_f32_e32 v141, v88
	v_exp_f32_e32 v150, v89
	v_exp_f32_e32 v142, v90
	v_exp_f32_e32 v149, v91
	v_exp_f32_e32 v143, v92
	v_exp_f32_e32 v148, v93
	v_exp_f32_e32 v144, v94
	v_exp_f32_e32 v147, v95
	v_exp_f32_e32 v145, v96
	v_exp_f32_e32 v146, v97
	v_fmamk_f32 v233, v66, 0x3e38aa3b, v224
	v_fmamk_f32 v234, v67, 0x3e38aa3b, v224
	v_fmamk_f32 v235, v68, 0x3e38aa3b, v224
	v_fmamk_f32 v236, v69, 0x3e38aa3b, v224
	v_fmamk_f32 v237, v70, 0x3e38aa3b, v224
	v_fmamk_f32 v226, v71, 0x3e38aa3b, v224
	v_fmamk_f32 v227, v72, 0x3e38aa3b, v224
	v_fmamk_f32 v228, v73, 0x3e38aa3b, v224
	v_fmamk_f32 v229, v74, 0x3e38aa3b, v224
	v_fmamk_f32 v230, v75, 0x3e38aa3b, v224
	v_fmamk_f32 v231, v76, 0x3e38aa3b, v224
	v_fmamk_f32 v232, v77, 0x3e38aa3b, v224
	v_fmamk_f32 v225, v78, 0x3e38aa3b, v224
	v_fmamk_f32 v238, v79, 0x3e38aa3b, v224
	v_fmamk_f32 v239, v80, 0x3e38aa3b, v224
	v_fmac_f32_e32 v224, 0x3e38aa3b, v81
	s_waitcnt lgkmcnt(0)
	s_barrier
	ds_write_b128 v214, v[114:117]
	ds_write_b128 v215, v[118:121]
	ds_read_b128 v[66:69], v212 offset:32768
	ds_read_b128 v[70:73], v212 offset:36864
	v_exp_f32_e32 v164, v233
	v_exp_f32_e32 v233, v224
	v_add_f32_e32 v224, v153, v138
	s_waitcnt lgkmcnt(1)
	v_mfma_f32_32x32x16_bf16 v[82:97], v[66:69], v[110:113], 0
	v_add_f32_e32 v224, v139, v224
	v_add_f32_e32 v224, v152, v224
	v_add_f32_e32 v224, v140, v224
	ds_read_b128 v[240:243], v216 offset:32768
	ds_read_b128 v[244:247], v216 offset:36864
	v_add_f32_e32 v224, v151, v224
	v_add_f32_e32 v224, v141, v224
	v_add_f32_e32 v224, v150, v224
	s_waitcnt lgkmcnt(2)
	v_mfma_f32_32x32x16_bf16 v[66:81], v[70:73], v[110:113], 0
	v_add_f32_e32 v224, v142, v224
	v_add_f32_e32 v224, v149, v224
	v_add_f32_e32 v224, v143, v224
	v_add_f32_e32 v224, v148, v224
	v_add_f32_e32 v224, v144, v224
	v_exp_f32_e32 v165, v234
	v_add_f32_e32 v224, v147, v224
	s_waitcnt lgkmcnt(1)
	v_mfma_f32_32x32x16_bf16 v[82:97], v[240:243], v[106:109], v[82:97]
	v_exp_f32_e32 v166, v235
	v_add_f32_e32 v224, v145, v224
	v_exp_f32_e32 v167, v236
	v_add_f32_e32 v224, v146, v224
	v_exp_f32_e32 v172, v237
	v_add_f32_e32 v224, v164, v224
	v_exp_f32_e32 v173, v226
	s_waitcnt lgkmcnt(0)
	v_mfma_f32_32x32x16_bf16 v[66:81], v[244:247], v[106:109], v[66:81]
	ds_read_b128 v[240:243], v217 offset:32768
	ds_read_b128 v[244:247], v217 offset:36864
	v_add_f32_e32 v224, v165, v224
	v_exp_f32_e32 v174, v227
	v_add_f32_e32 v224, v166, v224
	v_exp_f32_e32 v175, v228
	v_add_f32_e32 v224, v167, v224
	v_exp_f32_e32 v226, v229
	s_waitcnt lgkmcnt(1)
	v_mfma_f32_32x32x16_bf16 v[82:97], v[240:243], v[98:101], v[82:97]
	v_add_f32_e32 v224, v172, v224
	v_exp_f32_e32 v227, v230
	v_add_f32_e32 v224, v173, v224
	v_exp_f32_e32 v228, v231
	v_add_f32_e32 v224, v174, v224
	v_exp_f32_e32 v229, v232
	v_add_f32_e32 v224, v175, v224
	s_waitcnt lgkmcnt(0)
	v_mfma_f32_32x32x16_bf16 v[66:81], v[244:247], v[98:101], v[66:81]
	ds_read_b128 v[240:243], v218 offset:32768
	ds_read_b128 v[244:247], v218 offset:36864
	v_exp_f32_e32 v230, v225
	v_add_f32_e32 v224, v226, v224
	v_exp_f32_e32 v231, v238
	v_add_f32_e32 v224, v227, v224
	v_exp_f32_e32 v232, v239
	v_add_f32_e32 v224, v228, v224
	s_waitcnt lgkmcnt(1)
	v_mfma_f32_32x32x16_bf16 v[82:97], v[240:243], v[102:105], v[82:97]
	v_add_f32_e32 v224, v229, v224
	v_add_f32_e32 v224, v230, v224
	v_add_f32_e32 v224, v231, v224
	v_add_f32_e32 v224, v232, v224
	v_add_f32_e32 v224, v233, v224
	v_mov_b32_e32 v225, v224
	v_cvt_pk_bf16_f32 v138, v138, v153
	s_waitcnt lgkmcnt(0)
	v_mfma_f32_32x32x16_bf16 v[66:81], v[244:247], v[102:105], v[66:81]
	v_cvt_pk_bf16_f32 v139, v139, v152
	v_cvt_pk_bf16_f32 v140, v140, v151
	v_cvt_pk_bf16_f32 v141, v141, v150
	v_cvt_pk_bf16_f32 v142, v142, v149
	v_cvt_pk_bf16_f32 v143, v143, v148
	v_cvt_pk_bf16_f32 v144, v144, v147
	v_cvt_pk_bf16_f32 v145, v145, v146
	v_cvt_pk_bf16_f32 v146, v164, v165
	v_cvt_pk_bf16_f32 v147, v166, v167
	v_cvt_pk_bf16_f32 v148, v172, v173
	v_cvt_pk_bf16_f32 v149, v174, v175
	v_cvt_pk_bf16_f32 v150, v226, v227
	v_cvt_pk_bf16_f32 v151, v228, v229
	v_cvt_pk_bf16_f32 v152, v230, v231
	v_cvt_pk_bf16_f32 v153, v232, v233
	v_permlane32_swap_b32_e32 v224, v225
	s_cmp_gt_u32 s9, 60
	s_cselect_b64 s[4:5], -1, 0
	s_and_b64 vcc, exec, s[4:5]
	s_cbranch_vccnz .Lod_d1
	global_load_dwordx4 v[114:117], v[178:179], off offset:2048
	global_load_dwordx4 v[118:121], v[180:181], off offset:2048
	global_load_dwordx4 v[122:125], v[204:205], off offset:1024
	s_mov_b32 s6, 0xa0000
	s_mov_b32 s7, 0
	s_nop 0
	v_lshl_add_u64 v[178:179], v[178:179], 0, s[6:7]
	v_lshl_add_u64 v[180:181], v[180:181], 0, s[6:7]
	v_lshl_add_u64 v[204:205], v[204:205], 0, s[6:7]

; __device__ __forceinline__ void finishSM(f32x16& p0, f32x16& p1, float alpha, float& l_reg, bf16x8& pa0, bf16x8& pa1, bf16x8& pa2, bf16x8& pa3) {
; #pragma unroll
;   for (int r = 0; r < 16; ++r) p1[r] = __builtin_amdgcn_exp2f(p1[r]);
;   float ps = 0;
; #pragma unroll
;   for (int r = 0; r < 16; ++r) ps += p0[r];
; #pragma unroll
;   for (int r = 0; r < 16; ++r) ps += p1[r];
;   { auto rr = __builtin_amdgcn_permlane32_swap(__float_as_uint(ps), __float_as_uint(ps), false, false);
;     ps = __uint_as_float(rr[0]) + __uint_as_float(rr[1]); }
;   l_reg = l_reg * alpha + ps;
;     ...
;   PK4(p0, 0, pa0); PK4(p0, 8, pa1); PK4(p1, 0, pa2); PK4(p1, 8, pa3);
;     ...
; }
; template <int DK, bool QL>
; __device__ __forceinline__ void qkt(f32x16& p0, f32x16& p1, const bf16* Ks, const bf16x8* qr, const char* ql, int r32, int hi) {
;   p0 = f32x16{}; p1 = f32x16{};
; #pragma unroll
;   for (int d0 = 0; d0 < DK / 16; ++d0) { int cb = (d0 * 16 + hi * 8) * 2;
;     const bf16x8 qv = QL ? *reinterpret_cast<const bf16x8*>(ql + d0 * 1024) : qr[d0];
;     bf16x8 b0 = *reinterpret_cast<const bf16x8*>((const char*)Ks + kswz<DK>(r32, cb));
;     bf16x8 b1 = *reinterpret_cast<const bf16x8*>((const char*)Ks + kswz<DK>(32 + r32, cb));
;     p0 = __builtin_amdgcn_mfma_f32_32x32x16_bf16(b0, qv, p0, 0, 0, 0);
;     p1 = __builtin_amdgcn_mfma_f32_32x32x16_bf16(b1, qv, p1, 0, 0, 0); }
; }
; __device__ __forceinline__ void na_hook(f32x16& p0, f32x16& p1, int kr, int q_row, int q_col, int win_r, int win_c, const float* rpb, float inv_scale, int hi) {
;   const bool rowok = (kr >= win_r) && (kr < win_r + 8);
;   int ir = kr - q_row + 7; ir = ir < 0 ? 0 : (ir > 14 ? 14 : ir);
;   const float* rp = rpb + ir * 31;
; #pragma unroll
;   for (int r = 0; r < 16; ++r) {
;     const int kc = crow(r, hi);
;     { const bool ok = rowok && kc >= win_c && kc < win_c + 16; int ic = kc - q_col + 15; ic = ic < 0 ? 0 : (ic > 30 ? 30 : ic);
;       p0[r] = ok ? fmaf(rp[ic], inv_scale, p0[r]) : -1e30f; }
;     { const int kc2 = kc + 32; const bool ok = rowok && kc2 >= win_c && kc2 < win_c + 16; int ic = kc2 - q_col + 15; ic = ic < 0 ? 0 : (ic > 30 ? 30 : ic);
;       p1[r] = ok ? fmaf(rp[ic], inv_scale, p1[r]) : -1e30f; }
;   }
; }
; __device__ __forceinline__ int v_st(int k, int c) { const int kk = (k & ~0xC) | ((k & 4) << 1) | ((k & 8) >> 1); return ((kk >> 3) * 4 + (c >> 5)) * 512 + ((kk & 7) * 32 + (c & 31)) * 2; }
.LBB0_694:
	ds_write_b128 v214, v[182:185] offset:16384
	ds_write_b128 v215, v[194:197] offset:16384
	ds_read_b128 v[66:69], v212 offset:49152
	ds_read_b128 v[70:73], v212 offset:53248
	v_exp_f32_e32 v118, v140
	v_exp_f32_e32 v119, v141
	v_exp_f32_e32 v120, v134
	s_waitcnt lgkmcnt(1)
	v_mfma_f32_32x32x16_bf16 v[82:97], v[66:69], v[110:113], 0
	v_exp_f32_e32 v121, v135
	v_exp_f32_e32 v122, v132
	v_exp_f32_e32 v123, v133
	s_waitcnt lgkmcnt(0)
	v_mfma_f32_32x32x16_bf16 v[66:81], v[70:73], v[110:113], 0
	ds_read_b128 v[110:113], v216 offset:49152
	ds_read_b128 v[114:117], v216 offset:53248
	s_waitcnt lgkmcnt(1)
	v_mfma_f32_32x32x16_bf16 v[82:97], v[110:113], v[106:109], v[82:97]
	s_waitcnt lgkmcnt(0)
	v_mfma_f32_32x32x16_bf16 v[66:81], v[114:117], v[106:109], v[66:81]
	ds_read_b128 v[106:109], v217 offset:49152
	ds_read_b128 v[110:113], v217 offset:53248
	v_exp_f32_e32 v114, v128
	v_exp_f32_e32 v115, v129
	v_exp_f32_e32 v116, v126
	v_exp_f32_e32 v117, v127
	s_waitcnt lgkmcnt(1)
	v_mfma_f32_32x32x16_bf16 v[82:97], v[106:109], v[98:101], v[82:97]
	s_waitcnt lgkmcnt(0)
	v_mfma_f32_32x32x16_bf16 v[66:81], v[110:113], v[98:101], v[66:81]
	ds_read_b128 v[98:101], v218 offset:49152
	ds_read_b128 v[106:109], v218 offset:53248
	v_exp_f32_e32 v110, v136
	v_exp_f32_e32 v111, v137
	v_exp_f32_e32 v112, v130
	v_exp_f32_e32 v113, v131
	s_waitcnt lgkmcnt(1)
	v_mfma_f32_32x32x16_bf16 v[82:97], v[98:101], v[102:105], v[82:97]
	v_add_f32_e32 v98, 0, v177
	v_add_f32_e32 v98, v226, v98
	v_add_f32_e32 v98, v161, v98
	v_add_f32_e32 v98, v223, v98
	v_add_f32_e32 v98, v153, v98
	v_add_f32_e32 v98, v176, v98
	v_add_f32_e32 v98, v152, v98
	v_add_f32_e32 v98, v160, v98
	v_add_f32_e32 v98, v149, v98
	v_add_f32_e32 v98, v151, v98
	v_add_f32_e32 v98, v147, v98
	v_add_f32_e32 v98, v150, v98
	s_waitcnt lgkmcnt(0)
	v_mfma_f32_32x32x16_bf16 v[66:81], v[106:109], v[102:105], v[66:81]
	v_exp_f32_e32 v108, v138
	v_add_f32_e32 v98, v145, v98
	v_exp_f32_e32 v109, v139
	v_add_f32_e32 v98, v148, v98
	v_add_f32_e32 v98, v144, v98
	v_add_f32_e32 v98, v146, v98
	v_add_f32_e32 v98, v108, v98
	v_add_f32_e32 v98, v109, v98
	v_add_f32_e32 v98, v110, v98
	v_add_f32_e32 v98, v111, v98
	v_add_f32_e32 v98, v112, v98
	v_add_f32_e32 v98, v113, v98
	v_add_f32_e32 v98, v114, v98
	v_add_f32_e32 v98, v115, v98
	v_add_f32_e32 v98, v116, v98
	v_add_f32_e32 v98, v117, v98
	v_add_f32_e32 v98, v118, v98
	v_add_f32_e32 v98, v119, v98
	v_add_f32_e32 v98, v120, v98
	v_add_f32_e32 v98, v121, v98
	v_add_f32_e32 v98, v122, v98
	v_add_f32_e32 v98, v123, v98
	v_mov_b32_e32 v99, v98
	v_cvt_pk_bf16_f32 v100, v177, v226
	v_cvt_pk_bf16_f32 v101, v161, v223
	v_cvt_pk_bf16_f32 v102, v153, v176
	v_cvt_pk_bf16_f32 v103, v152, v160
	s_nop 1
	v_permlane32_swap_b32_e32 v98, v99
	v_cvt_pk_bf16_f32 v104, v149, v151
	v_cvt_pk_bf16_f32 v105, v147, v150
	v_cvt_pk_bf16_f32 v106, v145, v148
	v_cvt_pk_bf16_f32 v107, v144, v146
	v_cvt_pk_bf16_f32 v108, v108, v109
	v_cvt_pk_bf16_f32 v109, v110, v111
	v_cvt_pk_bf16_f32 v110, v112, v113
	v_cvt_pk_bf16_f32 v111, v114, v115
	v_cvt_pk_bf16_f32 v112, v116, v117
	v_cvt_pk_bf16_f32 v113, v118, v119
	v_cvt_pk_bf16_f32 v114, v120, v121
	v_cvt_pk_bf16_f32 v115, v122, v123
	s_nop 0
	ds_read_b64_tr_b16 v[116:117], v211 offset:0
	ds_read_b64_tr_b16 v[118:119], v211 offset:0x800
	ds_read_b64_tr_b16 v[120:121], v211 offset:0x1000
	ds_read_b64_tr_b16 v[122:123], v211 offset:0x1800
	ds_read_b64_tr_b16 v[124:125], v211 offset:0x2000
	ds_read_b64_tr_b16 v[126:127], v211 offset:0x2800
	ds_read_b64_tr_b16 v[128:129], v211 offset:0x3000
	ds_read_b64_tr_b16 v[130:131], v211 offset:0x3800
	s_waitcnt lgkmcnt(0)
	s_nop 0
	v_mfma_f32_32x32x16_bf16 v[18:33], v[100:103], v[116:119], v[18:33]
	ds_read_b64_tr_b16 v[116:117], v211 offset:0x200
	ds_read_b64_tr_b16 v[118:119], v211 offset:0xa00
	v_mfma_f32_32x32x16_bf16 v[18:33], v[104:107], v[120:123], v[18:33]
	ds_read_b64_tr_b16 v[120:121], v211 offset:0x1200
	ds_read_b64_tr_b16 v[122:123], v211 offset:0x1a00
	v_mfma_f32_32x32x16_bf16 v[18:33], v[108:111], v[124:127], v[18:33]
	ds_read_b64_tr_b16 v[124:125], v211 offset:0x2200
	ds_read_b64_tr_b16 v[126:127], v211 offset:0x2a00
	v_mfma_f32_32x32x16_bf16 v[18:33], v[112:115], v[128:131], v[18:33]
	ds_read_b64_tr_b16 v[128:129], v211 offset:0x3200
	ds_read_b64_tr_b16 v[130:131], v211 offset:0x3a00
	s_waitcnt lgkmcnt(0)
	v_mfma_f32_32x32x16_bf16 v[2:17], v[100:103], v[116:119], v[2:17]
	ds_read_b64_tr_b16 v[116:117], v211 offset:0x400
	ds_read_b64_tr_b16 v[118:119], v211 offset:0xc00
	v_mfma_f32_32x32x16_bf16 v[2:17], v[104:107], v[120:123], v[2:17]
	ds_read_b64_tr_b16 v[120:121], v211 offset:0x1400
	ds_read_b64_tr_b16 v[122:123], v211 offset:0x1c00
	v_mfma_f32_32x32x16_bf16 v[2:17], v[108:111], v[124:127], v[2:17]
	ds_read_b64_tr_b16 v[124:125], v211 offset:0x2400
	ds_read_b64_tr_b16 v[126:127], v211 offset:0x2c00
	v_mfma_f32_32x32x16_bf16 v[2:17], v[112:115], v[128:131], v[2:17]
	ds_read_b64_tr_b16 v[128:129], v211 offset:0x3400
	ds_read_b64_tr_b16 v[130:131], v211 offset:0x3c00
	s_waitcnt lgkmcnt(0)
	v_mfma_f32_32x32x16_bf16 v[50:65], v[100:103], v[116:119], v[50:65]
	ds_read_b64_tr_b16 v[116:117], v211 offset:0x600
	ds_read_b64_tr_b16 v[118:119], v211 offset:0xe00
	v_mfma_f32_32x32x16_bf16 v[50:65], v[104:107], v[120:123], v[50:65]
	ds_read_b64_tr_b16 v[120:121], v211 offset:0x1600
	ds_read_b64_tr_b16 v[122:123], v211 offset:0x1e00
	v_mfma_f32_32x32x16_bf16 v[50:65], v[108:111], v[124:127], v[50:65]
	ds_read_b64_tr_b16 v[124:125], v211 offset:0x2600
	ds_read_b64_tr_b16 v[126:127], v211 offset:0x2e00
	v_mfma_f32_32x32x16_bf16 v[50:65], v[112:115], v[128:131], v[50:65]
	ds_read_b64_tr_b16 v[128:129], v211 offset:0x3600
	ds_read_b64_tr_b16 v[130:131], v211 offset:0x3e00
	s_waitcnt lgkmcnt(0)
; #define SBAR() __builtin_amdgcn_sched_barrier(0)
; #define RESC(a) do { if (__any((a) < 1.f)) { if (hi == 0) al_l[r32] = (a); asm volatile("s_waitcnt lgkmcnt(0)" ::: "memory"); \
;     _Pragma("unroll") for (int d = 0; d < 4; ++d) _Pragma("unroll") for (int r = 0; r < 16; ++r) o[d][r] *= al_l[crow(r, hi)]; } } while (0)
; __device__ __forceinline__ void partialSM(f32x16& p0, f32x16& p1, float& m_reg, float& mn, float& alpha, float C, float thrRaw) {
;   float pmax = p0[0];
; #pragma unroll
;   for (int r = 1; r < 16; ++r) pmax = fmaxf(pmax, p0[r]);
; #pragma unroll
;   for (int r = 0; r < 16; ++r) pmax = fmaxf(pmax, p1[r]);
;   { auto rr = __builtin_amdgcn_permlane32_swap(__float_as_uint(pmax), __float_as_uint(pmax), false, false);
;     pmax = fmaxf(__uint_as_float(rr[0]), __uint_as_float(rr[1])); }
;   if (__builtin_expect(__all(pmax - m_reg <= thrRaw), 1)) { mn = m_reg; alpha = 1.f; }
;   else { mn = fmaxf(m_reg, pmax); alpha = __builtin_amdgcn_exp2f((m_reg - mn) * C); m_reg = mn; }
;   float mnC = -mn * C;
; #pragma unroll
;   for (int r = 0; r < 16; ++r) p0[r] = fmaf(p0[r], C, mnC);
; #pragma unroll
;   for (int r = 0; r < 16; ++r) p1[r] = fmaf(p1[r], C, mnC);
; #pragma unroll
;   for (int r = 0; r < 16; ++r) p0[r] = __builtin_amdgcn_exp2f(p0[r]);
; }
; __device__ __forceinline__ void finishSM(f32x16& p0, f32x16& p1, float alpha, float& l_reg, bf16x8& pa0, bf16x8& pa1, bf16x8& pa2, bf16x8& pa3) {
; #pragma unroll
;   for (int r = 0; r < 16; ++r) p1[r] = __builtin_amdgcn_exp2f(p1[r]);
;   float ps = 0;
; #pragma unroll
;   for (int r = 0; r < 16; ++r) ps += p0[r];
; #pragma unroll
;   for (int r = 0; r < 16; ++r) ps += p1[r];
;   { auto rr = __builtin_amdgcn_permlane32_swap(__float_as_uint(ps), __float_as_uint(ps), false, false);
;     ps = __uint_as_float(rr[0]) + __uint_as_float(rr[1]); }
;   l_reg = l_reg * alpha + ps;
;     ...
;   PK4(p0, 0, pa0); PK4(p0, 8, pa1); PK4(p1, 0, pa2); PK4(p1, 8, pa3);
;     ...
; }
; template <int DK, bool NA, bool QL, int SD> ...
;     ...
;   pv_d0(o, vb0, pa0, pa1, pa2, pa3); partialSM(pB0, pB1, m_reg, mnB, alB, C, thrRaw);
;   __syncthreads(); RESC(alB);
;   finishSM(pB0, pB1, alB, l_reg, pa0, pa1, pa2, pa3); SBAR();
	v_mfma_f32_32x32x16_bf16 v[34:49], v[100:103], v[116:119], v[34:49]
	v_max_f32_e32 v100, v83, v83
	v_max_f32_e32 v101, v82, v82
	v_max_f32_e32 v100, v101, v100
	v_max3_f32 v100, v100, v84, v85
	v_max3_f32 v100, v100, v86, v87
	v_max3_f32 v100, v100, v88, v89
	v_max3_f32 v100, v100, v90, v91
	v_max3_f32 v100, v100, v92, v93
	v_max3_f32 v100, v100, v94, v95
	v_mfma_f32_32x32x16_bf16 v[34:49], v[104:107], v[120:123], v[34:49]
	v_max3_f32 v100, v100, v96, v97
	v_max3_f32 v100, v100, v66, v67
	v_max3_f32 v100, v100, v68, v69
	v_max3_f32 v100, v100, v70, v71
	v_max3_f32 v100, v100, v72, v73
	v_max3_f32 v100, v100, v74, v75
	v_max3_f32 v100, v100, v76, v77
	v_max3_f32 v100, v100, v78, v79
	v_mfma_f32_32x32x16_bf16 v[34:49], v[108:111], v[124:127], v[34:49]
	v_max3_f32 v100, v100, v80, v81
	v_mov_b32_e32 v101, v100
	s_nop 1
	v_permlane32_swap_b32_e32 v100, v101
	v_max_f32_e32 v101, v101, v101
	v_max_f32_e32 v100, v100, v100
	v_max_f32_e32 v100, v100, v101
	v_sub_f32_e32 v101, v100, v142
	s_mov_b32 s2, 0x42800000
	v_cmp_ge_f32_e32 vcc, s2, v101
	v_max_f32_e32 v101, v142, v142
	v_max_f32_e32 v101, v101, v100
	v_mfma_f32_32x32x16_bf16 v[34:49], v[112:115], v[128:131], v[34:49]
	v_sub_f32_e32 v100, v142, v101
	v_mul_f32_e32 v100, 0x3e38aa3b, v100
	v_exp_f32_e32 v100, v100
	s_cmp_eq_u64 vcc, exec
	s_cselect_b64 s[2:3], -1, 0
	v_cndmask_b32_e64 v100, v100, 1.0, s[2:3]
	v_cmp_gt_f32_e32 vcc, 1.0, v100
	s_barrier
	s_cbranch_vccz .LBB0_698
	s_and_saveexec_b64 s[4:5], s[0:1]
	ds_write_b32 v208, v100 offset:128
	s_or_b64 exec, exec, s[4:5]
	s_waitcnt lgkmcnt(0)
	v_add_u32_e32 v114, v207, v0
	ds_read_b128 v[102:105], v114 offset:224
	ds_read_b128 v[106:109], v114 offset:192
	ds_read_b128 v[110:113], v114 offset:160
	ds_read_b128 v[114:117], v114 offset:128
	s_waitcnt lgkmcnt(3)
	v_pk_mul_f32 v[30:31], v[30:31], v[102:103]
	s_waitcnt lgkmcnt(2)
	v_pk_mul_f32 v[26:27], v[26:27], v[106:107]
	s_waitcnt lgkmcnt(1)
	v_pk_mul_f32 v[22:23], v[22:23], v[110:111]
	v_pk_mul_f32 v[32:33], v[32:33], v[104:105]
	v_pk_mul_f32 v[28:29], v[28:29], v[108:109]
	v_pk_mul_f32 v[24:25], v[24:25], v[112:113]
	s_waitcnt lgkmcnt(0)
	v_pk_mul_f32 v[20:21], v[20:21], v[116:117]
	v_pk_mul_f32 v[18:19], v[18:19], v[114:115]
	v_pk_mul_f32 v[14:15], v[102:103], v[14:15]
	v_pk_mul_f32 v[10:11], v[106:107], v[10:11]
	v_pk_mul_f32 v[6:7], v[110:111], v[6:7]
	v_pk_mul_f32 v[16:17], v[104:105], v[16:17]
	v_pk_mul_f32 v[12:13], v[108:109], v[12:13]
	v_pk_mul_f32 v[8:9], v[112:113], v[8:9]
	v_pk_mul_f32 v[4:5], v[116:117], v[4:5]
	v_pk_mul_f32 v[2:3], v[114:115], v[2:3]
	v_pk_mul_f32 v[62:63], v[102:103], v[62:63]
	v_pk_mul_f32 v[58:59], v[106:107], v[58:59]
	v_pk_mul_f32 v[54:55], v[110:111], v[54:55]
	v_pk_mul_f32 v[64:65], v[104:105], v[64:65]
	v_pk_mul_f32 v[60:61], v[108:109], v[60:61]
	v_pk_mul_f32 v[56:57], v[112:113], v[56:57]
	v_pk_mul_f32 v[52:53], v[116:117], v[52:53]
	v_pk_mul_f32 v[50:51], v[114:115], v[50:51]
	v_pk_mul_f32 v[46:47], v[102:103], v[46:47]
	v_pk_mul_f32 v[42:43], v[106:107], v[42:43]
	v_pk_mul_f32 v[38:39], v[110:111], v[38:39]
	v_pk_mul_f32 v[48:49], v[104:105], v[48:49]
	v_pk_mul_f32 v[44:45], v[108:109], v[44:45]
	v_pk_mul_f32 v[40:41], v[112:113], v[40:41]
	v_pk_mul_f32 v[36:37], v[116:117], v[36:37]
	v_pk_mul_f32 v[34:35], v[114:115], v[34:35]
.LBB0_698:
	v_cndmask_b32_e64 v101, v101, v142, s[2:3]
	v_mul_f32_e32 v101, 0xbe38aa3b, v101
	v_fmamk_f32 v82, v82, 0x3e38aa3b, v101
	v_fmamk_f32 v83, v83, 0x3e38aa3b, v101
	v_fmamk_f32 v102, v84, 0x3e38aa3b, v101
	v_exp_f32_e32 v84, v82
	v_fmamk_f32 v103, v86, 0x3e38aa3b, v101
	v_exp_f32_e32 v86, v83
	v_fmamk_f32 v85, v85, 0x3e38aa3b, v101
	v_exp_f32_e32 v82, v102
	v_fmamk_f32 v66, v66, 0x3e38aa3b, v101
	v_exp_f32_e32 v85, v85
	v_fmamk_f32 v104, v87, 0x3e38aa3b, v101
	v_fmamk_f32 v113, v96, 0x3e38aa3b, v101
	v_fmamk_f32 v96, v77, 0x3e38aa3b, v101
	v_exp_f32_e32 v77, v103
	v_exp_f32_e32 v102, v66
	v_add_f32_e32 v66, 0, v84
	v_fmamk_f32 v105, v88, 0x3e38aa3b, v101
	v_exp_f32_e32 v83, v104
	v_add_f32_e32 v66, v86, v66
	v_fmamk_f32 v106, v89, 0x3e38aa3b, v101
	v_fmamk_f32 v112, v95, 0x3e38aa3b, v101
	v_fmamk_f32 v95, v76, 0x3e38aa3b, v101
	v_exp_f32_e32 v76, v105
	v_add_f32_e32 v66, v82, v66
	v_fmamk_f32 v107, v90, 0x3e38aa3b, v101
	v_fmamk_f32 v114, v97, 0x3e38aa3b, v101
	v_fmamk_f32 v97, v78, 0x3e38aa3b, v101
	v_exp_f32_e32 v78, v106
	v_add_f32_e32 v66, v85, v66
	v_fmamk_f32 v108, v91, 0x3e38aa3b, v101
	v_fmamk_f32 v109, v92, 0x3e38aa3b, v101
	v_fmamk_f32 v92, v73, 0x3e38aa3b, v101
	v_exp_f32_e32 v73, v107
	v_add_f32_e32 v66, v77, v66
	v_fmamk_f32 v111, v94, 0x3e38aa3b, v101
	v_fmamk_f32 v94, v75, 0x3e38aa3b, v101
	v_exp_f32_e32 v75, v108
	v_add_f32_e32 v66, v83, v66
	v_fmamk_f32 v110, v93, 0x3e38aa3b, v101
	v_fmamk_f32 v90, v71, 0x3e38aa3b, v101
	v_exp_f32_e32 v71, v109
	v_add_f32_e32 v66, v76, v66
	v_fmamk_f32 v93, v74, 0x3e38aa3b, v101
	v_exp_f32_e32 v74, v110
	v_add_f32_e32 v66, v78, v66
	v_fmamk_f32 v88, v69, 0x3e38aa3b, v101
	v_exp_f32_e32 v69, v111
	v_add_f32_e32 v66, v73, v66
	v_fmamk_f32 v91, v72, 0x3e38aa3b, v101
	v_exp_f32_e32 v72, v112
	v_add_f32_e32 v66, v75, v66
	v_fmamk_f32 v87, v68, 0x3e38aa3b, v101
	v_exp_f32_e32 v68, v113
	v_add_f32_e32 v66, v71, v66
	v_fmamk_f32 v89, v70, 0x3e38aa3b, v101
	v_exp_f32_e32 v70, v114
	v_add_f32_e32 v66, v74, v66
	v_fmamk_f32 v67, v67, 0x3e38aa3b, v101
	v_add_f32_e32 v66, v69, v66
	v_exp_f32_e32 v103, v67
	v_add_f32_e32 v66, v72, v66
	v_exp_f32_e32 v87, v87
	v_add_f32_e32 v66, v68, v66
	v_exp_f32_e32 v88, v88
	v_add_f32_e32 v66, v70, v66
	v_exp_f32_e32 v89, v89
	v_add_f32_e32 v66, v102, v66
	v_exp_f32_e32 v90, v90
	v_add_f32_e32 v66, v103, v66
	v_exp_f32_e32 v91, v91
; __device__ __forceinline__ void finishSM(f32x16& p0, f32x16& p1, float alpha, float& l_reg, bf16x8& pa0, bf16x8& pa1, bf16x8& pa2, bf16x8& pa3) {
; #pragma unroll
;   for (int r = 0; r < 16; ++r) p1[r] = __builtin_amdgcn_exp2f(p1[r]);
;   float ps = 0;
; #pragma unroll
;   for (int r = 0; r < 16; ++r) ps += p0[r];
; #pragma unroll
;   for (int r = 0; r < 16; ++r) ps += p1[r];
;   { auto rr = __builtin_amdgcn_permlane32_swap(__float_as_uint(ps), __float_as_uint(ps), false, false);
;     ps = __uint_as_float(rr[0]) + __uint_as_float(rr[1]); }
;   l_reg = l_reg * alpha + ps;
;     ...
;   PK4(p0, 0, pa0); PK4(p0, 8, pa1); PK4(p1, 0, pa2); PK4(p1, 8, pa3);
;     ...
; }
; template <int DK, bool QL>
; __device__ __forceinline__ void qkt(f32x16& p0, f32x16& p1, const bf16* Ks, const bf16x8* qr, const char* ql, int r32, int hi) {
;   p0 = f32x16{}; p1 = f32x16{};
; #pragma unroll
;   for (int d0 = 0; d0 < DK / 16; ++d0) { int cb = (d0 * 16 + hi * 8) * 2;
;     const bf16x8 qv = QL ? *reinterpret_cast<const bf16x8*>(ql + d0 * 1024) : qr[d0];
;     bf16x8 b0 = *reinterpret_cast<const bf16x8*>((const char*)Ks + kswz<DK>(r32, cb));
;     bf16x8 b1 = *reinterpret_cast<const bf16x8*>((const char*)Ks + kswz<DK>(32 + r32, cb));
;     p0 = __builtin_amdgcn_mfma_f32_32x32x16_bf16(b0, qv, p0, 0, 0, 0);
;     p1 = __builtin_amdgcn_mfma_f32_32x32x16_bf16(b1, qv, p1, 0, 0, 0); }
; }
; __device__ __forceinline__ void na_hook(f32x16& p0, f32x16& p1, int kr, int q_row, int q_col, int win_r, int win_c, const float* rpb, float inv_scale, int hi) {
;   const bool rowok = (kr >= win_r) && (kr < win_r + 8);
;   int ir = kr - q_row + 7; ir = ir < 0 ? 0 : (ir > 14 ? 14 : ir);
;   const float* rp = rpb + ir * 31;
; #pragma unroll
;   for (int r = 0; r < 16; ++r) {
;     const int kc = crow(r, hi);
;     { const bool ok = rowok && kc >= win_c && kc < win_c + 16; int ic = kc - q_col + 15; ic = ic < 0 ? 0 : (ic > 30 ? 30 : ic);
;       p0[r] = ok ? fmaf(rp[ic], inv_scale, p0[r]) : -1e30f; }
;     { const int kc2 = kc + 32; const bool ok = rowok && kc2 >= win_c && kc2 < win_c + 16; int ic = kc2 - q_col + 15; ic = ic < 0 ? 0 : (ic > 30 ? 30 : ic);
;       p1[r] = ok ? fmaf(rp[ic], inv_scale, p1[r]) : -1e30f; }
;   }
; }
; __device__ __forceinline__ int v_st(int k, int c) { const int kk = (k & ~0xC) | ((k & 4) << 1) | ((k & 8) >> 1); return ((kk >> 3) * 4 + (c >> 5)) * 512 + ((kk & 7) * 32 + (c & 31)) * 2; }
	v_add_f32_e32 v66, v87, v66
	v_exp_f32_e32 v92, v92
	v_add_f32_e32 v66, v88, v66
	v_exp_f32_e32 v93, v93
	v_add_f32_e32 v66, v89, v66
	v_exp_f32_e32 v94, v94
	v_add_f32_e32 v66, v90, v66
	v_exp_f32_e32 v95, v95
	v_add_f32_e32 v66, v91, v66
	v_exp_f32_e32 v96, v96
	v_add_f32_e32 v66, v92, v66
	v_fmamk_f32 v79, v79, 0x3e38aa3b, v101
	v_exp_f32_e32 v97, v97
	v_add_f32_e32 v66, v93, v66
	v_fmamk_f32 v80, v80, 0x3e38aa3b, v101
	v_exp_f32_e32 v104, v79
	v_add_f32_e32 v66, v94, v66
	v_fmac_f32_e32 v101, 0x3e38aa3b, v81
	v_exp_f32_e32 v105, v80
	v_add_f32_e32 v66, v95, v66
	v_exp_f32_e32 v101, v101
	v_add_f32_e32 v66, v96, v66
	v_add_f32_e32 v66, v97, v66
	v_add_f32_e32 v66, v104, v66
	v_add_f32_e32 v66, v105, v66
	v_add_f32_e32 v66, v101, v66
	v_mov_b32_e32 v67, v66
	s_nop 1
	v_permlane32_swap_b32_e32 v66, v67
	v_cvt_pk_bf16_f32 v80, v84, v86
	v_cvt_pk_bf16_f32 v81, v82, v85
	v_cvt_pk_bf16_f32 v82, v77, v83
	v_cvt_pk_bf16_f32 v83, v76, v78
	v_cvt_pk_bf16_f32 v76, v73, v75
	v_cvt_pk_bf16_f32 v77, v71, v74
	v_cvt_pk_bf16_f32 v78, v69, v72
	v_cvt_pk_bf16_f32 v79, v68, v70
	v_cvt_pk_bf16_f32 v68, v102, v103
	v_cvt_pk_bf16_f32 v69, v87, v88
	v_cvt_pk_bf16_f32 v70, v89, v90
	v_cvt_pk_bf16_f32 v71, v91, v92
	v_cvt_pk_bf16_f32 v72, v93, v94
	v_cvt_pk_bf16_f32 v73, v95, v96
	v_cvt_pk_bf16_f32 v74, v97, v104
	v_cvt_pk_bf16_f32 v75, v105, v101
	s_nop 0
	ds_read_b64_tr_b16 v[84:85], v210 offset:0
	ds_read_b64_tr_b16 v[86:87], v210 offset:0x800
	ds_read_b64_tr_b16 v[88:89], v210 offset:0x1000
	ds_read_b64_tr_b16 v[90:91], v210 offset:0x1800
	ds_read_b64_tr_b16 v[92:93], v210 offset:0x2000
	ds_read_b64_tr_b16 v[94:95], v210 offset:0x2800
	ds_read_b64_tr_b16 v[102:103], v210 offset:0x3000
	ds_read_b64_tr_b16 v[104:105], v210 offset:0x3800
	s_waitcnt lgkmcnt(0)
	s_nop 0
	v_mfma_f32_32x32x16_bf16 v[18:33], v[80:83], v[84:87], v[18:33]
	ds_read_b64_tr_b16 v[84:85], v210 offset:0x200
	ds_read_b64_tr_b16 v[86:87], v210 offset:0xa00
	v_mfma_f32_32x32x16_bf16 v[18:33], v[76:79], v[88:91], v[18:33]
	ds_read_b64_tr_b16 v[88:89], v210 offset:0x1200
	ds_read_b64_tr_b16 v[90:91], v210 offset:0x1a00
	v_mfma_f32_32x32x16_bf16 v[18:33], v[68:71], v[92:95], v[18:33]
	ds_read_b64_tr_b16 v[92:93], v210 offset:0x2200
	ds_read_b64_tr_b16 v[94:95], v210 offset:0x2a00
	v_mfma_f32_32x32x16_bf16 v[18:33], v[72:75], v[102:105], v[18:33]
	ds_read_b64_tr_b16 v[102:103], v210 offset:0x3200
	ds_read_b64_tr_b16 v[104:105], v210 offset:0x3a00
	s_waitcnt lgkmcnt(0)
	v_mfma_f32_32x32x16_bf16 v[2:17], v[80:83], v[84:87], v[2:17]
	ds_read_b64_tr_b16 v[84:85], v210 offset:0x400
	ds_read_b64_tr_b16 v[86:87], v210 offset:0xc00
	v_mfma_f32_32x32x16_bf16 v[2:17], v[76:79], v[88:91], v[2:17]
	ds_read_b64_tr_b16 v[88:89], v210 offset:0x1400
	ds_read_b64_tr_b16 v[90:91], v210 offset:0x1c00
	v_mfma_f32_32x32x16_bf16 v[2:17], v[68:71], v[92:95], v[2:17]
	ds_read_b64_tr_b16 v[92:93], v210 offset:0x2400
	ds_read_b64_tr_b16 v[94:95], v210 offset:0x2c00
	v_mfma_f32_32x32x16_bf16 v[2:17], v[72:75], v[102:105], v[2:17]
	ds_read_b64_tr_b16 v[102:103], v210 offset:0x3400
	ds_read_b64_tr_b16 v[104:105], v210 offset:0x3c00
	s_waitcnt lgkmcnt(0)
	v_mfma_f32_32x32x16_bf16 v[50:65], v[80:83], v[84:87], v[50:65]
	ds_read_b64_tr_b16 v[84:85], v210 offset:0x600
	ds_read_b64_tr_b16 v[86:87], v210 offset:0xe00
	v_mfma_f32_32x32x16_bf16 v[50:65], v[76:79], v[88:91], v[50:65]
	ds_read_b64_tr_b16 v[88:89], v210 offset:0x1600
	ds_read_b64_tr_b16 v[90:91], v210 offset:0x1e00
	v_mfma_f32_32x32x16_bf16 v[50:65], v[68:71], v[92:95], v[50:65]
	ds_read_b64_tr_b16 v[92:93], v210 offset:0x2600
	ds_read_b64_tr_b16 v[94:95], v210 offset:0x2e00
	v_mfma_f32_32x32x16_bf16 v[50:65], v[72:75], v[102:105], v[50:65]
	ds_read_b64_tr_b16 v[102:103], v210 offset:0x3600
	ds_read_b64_tr_b16 v[104:105], v210 offset:0x3e00
	s_waitcnt lgkmcnt(0)
	v_mfma_f32_32x32x16_bf16 v[34:49], v[80:83], v[84:87], v[34:49]
	v_mfma_f32_32x32x16_bf16 v[34:49], v[76:79], v[88:91], v[34:49]
	v_mfma_f32_32x32x16_bf16 v[34:49], v[68:71], v[92:95], v[34:49]
	v_mfma_f32_32x32x16_bf16 v[34:49], v[72:75], v[102:105], v[34:49]
	s_and_saveexec_b64 s[2:3], s[0:1]
	v_add_f32_e32 v68, v98, v99
	v_fmac_f32_e32 v68, v209, v143
	v_add_f32_e32 v66, v66, v67
	v_fmac_f32_e32 v66, v68, v100
	ds_write_b32 v208, v66
	s_or_b64 exec, exec, s[2:3]
	s_waitcnt vmcnt(0) lgkmcnt(0)
	v_add_u32_e32 v0, v207, v0
	ds_read_b128 v[66:69], v0
	ds_read_b128 v[70:73], v0 offset:32
	v_readlane_b32 s0, v253, 17
	v_readlane_b32 s1, v253, 18
	s_movk_i32 s3, 0x2800
	s_waitcnt lgkmcnt(1)
	v_rcp_f32_e32 v66, v66
	v_rcp_f32_e32 v67, v67
	s_cmp_lg_u32 0, -1
	s_cselect_b32 s2, 0, 0
	v_mul_f32_e32 v75, v66, v2
	v_rcp_f32_e32 v2, v68
	v_mul_f32_e32 v68, v67, v3
	v_rcp_f32_e32 v3, v69
	v_mul_f32_e32 v74, v66, v18
	v_mul_f32_e32 v50, v66, v50
	v_mul_f32_e32 v34, v66, v34
	v_mul_f32_e32 v66, v67, v19
	v_mul_f32_e32 v51, v67, v51
	v_mul_f32_e32 v35, v67, v35
	v_mul_f32_e32 v67, v2, v20
	v_mul_f32_e32 v69, v2, v4
	v_mul_f32_e32 v52, v2, v52
	v_mul_f32_e32 v36, v2, v36
	v_mul_f32_e32 v76, v3, v21
	s_waitcnt lgkmcnt(0)
	v_rcp_f32_e32 v2, v70
	v_mul_f32_e32 v70, v3, v5
	v_mul_f32_e32 v53, v3, v53
	v_mul_f32_e32 v37, v3, v37
	v_rcp_f32_e32 v3, v71
	v_mul_f32_e32 v22, v2, v22
	v_mul_f32_e32 v6, v2, v6
	v_mul_f32_e32 v54, v2, v54
	v_mul_f32_e32 v38, v2, v38
	v_mul_f32_e32 v23, v3, v23
	v_mul_f32_e32 v7, v3, v7
	v_mul_f32_e32 v55, v3, v55
	v_mul_f32_e32 v39, v3, v39
	ds_read_b128 v[2:5], v0 offset:64
	v_rcp_f32_e32 v18, v72
	v_rcp_f32_e32 v71, v73
	s_mov_b32 s12, s13
	s_mov_b32 s14, s13
	v_mul_f32_e32 v24, v18, v24
	v_mul_f32_e32 v8, v18, v8
	v_mul_f32_e32 v56, v18, v56
	v_mul_f32_e32 v40, v18, v40
	ds_read_b128 v[18:21], v0 offset:96
	s_waitcnt lgkmcnt(1)
; __device__ __forceinline__ int opaque_tid() { int t = threadIdx.x; asm volatile("" : "+v"(t)); return t; }
; __device__ __forceinline__ unsigned cvtpk(float lo, float hi) { unsigned r; asm volatile("v_cvt_pk_bf16_f32 %0, %1, %2" : "=v"(r) : "v"(lo), "v"(hi)); return r; }
; __device__ __forceinline__ int v_st(int k, int c) { const int kk = (k & ~0xC) | ((k & 4) << 1) | ((k & 8) >> 1); return ((kk >> 3) * 4 + (c >> 5)) * 512 + ((kk & 7) * 32 + (c & 31)) * 2; }
; __device__ __forceinline__ int v_rd_base(int lane) { return ((lane & 3) << 3) | (((lane >> 2) & 3) << 6) | (((lane >> 4) & 1) << 5) | (((lane >> 5) & 1) << 8); }
; #define HOOK(P0, P1, j) do { if (NA) na_hook(P0, P1, krow0 + (j), q_row, q_col, win_r, win_c, rpb, inv_scale, hi); } while (0)
; template <int DK, bool NA, bool QL, int SD> ...
;     ...
;   const bf16* Qw = Qb + (long)(wid * 32 + r32) * LDP + hi * 8;
; #pragma unroll
;   for (int d0 = 0; d0 < DK / 16; ++d0) { const bf16x8 qv = *reinterpret_cast<const bf16x8*>(Qw + d0 * 16); if (QL) *reinterpret_cast<bf16x8*>(ql + d0 * 1024) = qv; else qr[d0] = qv; }
;   const int sr = tid >> 4, sc = (tid & 15) * 8, vst0 = v_st(sr, sc), vst1 = v_st(32 + sr, sc);
;   const int ksr = DK == 128 ? sr : (tid >> 3), ksc = DK == 128 ? sc : (tid & 7) * 8;
;   const int vb0 = (int)(uintptr_t)V_lds + v_rd_base(lane);
;   struct { bf16x8 vs0, vs1, ks0, ks1; } sr_[SD];
;     ...
;   f32x16 pA0, pA1, pB0, pB1; float mnA, mnB, alA, alB; bf16x8 pa0, pa1, pa2, pa3;
;   constexpr int SE = 0, SO = SD - 1;
;   SLOAD(SE, 0); asm volatile("s_waitcnt vmcnt(0)" ::: "memory"); SWRITE(0, SE); __syncthreads();
;   qkt<DK, QL>(pA0, pA1, K_lds, qr, ql, r32, hi); HOOK(pA0, pA1, 0); partialSM(pA0, pA1, m_reg, mnA, alA, C, thrRaw);
;   SLOAD(SO, KVBLK); if (SD == 2) { if (2 < NT) SLOAD(SE, 2 * KVBLK); }
; __global__ void __launch_bounds__(NTHR) mega_fwd(Params p) {
;     ...
;                     { const int t2 = opaque_tid(); v4u* STv = (v4u*)((char*)lds + 69632) + t2;
; #pragma unroll
;                       for (int k = 0; k < 8; ++k) { const int d = k >> 1, r0 = 8 * (k & 1); v4u w;
;                           w.x = att::cvtpk(o[d][r0], o[d][r0 + 1]); w.y = att::cvtpk(o[d][r0 + 2], o[d][r0 + 3]); w.z = att::cvtpk(o[d][r0 + 4], o[d][r0 + 5]); w.w = att::cvtpk(o[d][r0 + 6], o[d][r0 + 7]);
;                           STv[k * 512] = w; } }
	v_rcp_f32_e32 v0, v2
	v_rcp_f32_e32 v2, v3
	v_rcp_f32_e32 v3, v4
	v_mul_f32_e32 v25, v71, v25
	v_mul_f32_e32 v26, v0, v26
	v_mul_f32_e32 v10, v0, v10
	v_mul_f32_e32 v58, v0, v58
	v_mul_f32_e32 v0, v0, v42
	v_mul_f32_e32 v27, v2, v27
	v_mul_f32_e32 v11, v2, v11
	v_mul_f32_e32 v42, v2, v59
	v_mul_f32_e32 v43, v2, v43
	v_rcp_f32_e32 v2, v5
	v_mul_f32_e32 v28, v3, v28
	v_mul_f32_e32 v12, v3, v12
	v_mul_f32_e32 v59, v3, v60
	v_mul_f32_e32 v44, v3, v44
	v_mul_f32_e32 v29, v2, v29
	s_waitcnt lgkmcnt(0)
	v_rcp_f32_e32 v3, v18
	v_mul_f32_e32 v13, v2, v13
	v_mul_f32_e32 v18, v2, v61
	v_mul_f32_e32 v45, v2, v45
	v_rcp_f32_e32 v2, v19
	v_mul_f32_e32 v30, v3, v30
	v_mul_f32_e32 v14, v3, v14
	v_mul_f32_e32 v19, v3, v62
	v_mul_f32_e32 v46, v3, v46
	v_mul_f32_e32 v31, v2, v31
	v_rcp_f32_e32 v3, v20
	v_mul_f32_e32 v15, v2, v15
	v_mul_f32_e32 v20, v2, v63
	v_mul_f32_e32 v47, v2, v47
	v_rcp_f32_e32 v2, v21
	v_mul_f32_e32 v32, v3, v32
	v_mul_f32_e32 v16, v3, v16
	v_mul_f32_e32 v21, v3, v64
	v_mul_f32_e32 v33, v2, v33
	v_mul_f32_e32 v17, v2, v17
	v_mul_f32_e32 v60, v2, v65
	v_mul_f32_e32 v49, v2, v49
	v_mov_b32_e32 v2, v188
	v_mul_f32_e32 v48, v3, v48
	v_lshl_add_u32 v2, v2, 4, 0
	v_add_u32_e32 v61, 0x11000, v2
	v_cvt_pk_bf16_f32 v2, v74, v66
	v_cvt_pk_bf16_f32 v3, v67, v76
	v_cvt_pk_bf16_f32 v4, v22, v23
	v_cvt_pk_bf16_f32 v5, v24, v25
	ds_write_b128 v61, v[2:5]
	v_cvt_pk_bf16_f32 v2, v26, v27
	v_cvt_pk_bf16_f32 v3, v28, v29
	v_cvt_pk_bf16_f32 v4, v30, v31
	v_cvt_pk_bf16_f32 v5, v32, v33
	v_mul_f32_e32 v9, v71, v9
	ds_write_b128 v61, v[2:5] offset:8192
	v_cvt_pk_bf16_f32 v2, v75, v68
	v_cvt_pk_bf16_f32 v3, v69, v70
	v_cvt_pk_bf16_f32 v4, v6, v7
	v_cvt_pk_bf16_f32 v5, v8, v9
	ds_write_b128 v61, v[2:5] offset:16384
	v_cvt_pk_bf16_f32 v2, v10, v11
	v_cvt_pk_bf16_f32 v3, v12, v13
	v_cvt_pk_bf16_f32 v4, v14, v15
	v_cvt_pk_bf16_f32 v5, v16, v17
	v_mul_f32_e32 v57, v71, v57
	ds_write_b128 v61, v[2:5] offset:24576
	v_cvt_pk_bf16_f32 v2, v50, v51
	v_cvt_pk_bf16_f32 v3, v52, v53
	v_cvt_pk_bf16_f32 v4, v54, v55
	v_cvt_pk_bf16_f32 v5, v56, v57
	ds_write_b128 v61, v[2:5] offset:32768
	v_cvt_pk_bf16_f32 v2, v58, v42
	v_cvt_pk_bf16_f32 v3, v59, v18
	v_cvt_pk_bf16_f32 v4, v19, v20
	v_cvt_pk_bf16_f32 v5, v21, v60
	v_mul_f32_e32 v41, v71, v41
	ds_write_b128 v61, v[2:5] offset:40960
	v_cvt_pk_bf16_f32 v2, v34, v35
	v_cvt_pk_bf16_f32 v3, v36, v37
	v_cvt_pk_bf16_f32 v4, v38, v39
	v_cvt_pk_bf16_f32 v5, v40, v41
	v_mov_b32_e32 v74, v188
	ds_write_b128 v61, v[2:5] offset:49152
	v_cvt_pk_bf16_f32 v2, v0, v43
	v_cvt_pk_bf16_f32 v3, v44, v45
	v_cvt_pk_bf16_f32 v4, v46, v47
	v_cvt_pk_bf16_f32 v5, v48, v49
	ds_write_b128 v61, v[2:5] offset:57344
	v_mov_b64_e32 v[50:51], s[0:1]
	v_ashrrev_i32_e32 v75, 4, v74
	v_lshrrev_b32_e32 v162, 2, v75
	v_lshrrev_b32_e32 v155, 3, v75
	v_xor_b32_e32 v162, v162, v155
	v_and_b32_e32 v162, 1, v162
	v_mul_u32_u24_e32 v162, 12, v162
	v_xor_b32_e32 v155, v75, v162
	v_lshlrev_b32_e32 v16, 3, v74
	v_and_b32_e32 v0, 0x78, v16
	v_add_u32_e32 v17, 32, v75
	v_mad_i64_i32 v[2:3], s[0:1], v155, s3, v[50:51]
	v_lshlrev_b32_e32 v52, 1, v0
	v_mov_b32_e32 v53, v1
	v_add_u32_e32 v162, 32, v155
	v_mad_i64_i32 v[4:5], s[0:1], v162, s3, v[50:51]
	v_ashrrev_i32_e32 v72, 3, v74
	v_lshl_add_u64 v[2:3], v[2:3], 0, v[52:53]
	v_lshl_add_u64 v[6:7], v[4:5], 0, v[52:53]
	v_lshlrev_b32_e32 v22, 4, v74
	global_load_dwordx4 v[2:5], v[2:3], off offset:2048
	s_nop 0
	global_load_dwordx4 v[6:9], v[6:7], off offset:2048
	v_mad_i64_i32 v[10:11], s[0:1], v72, s3, v[50:51]
	v_and_b32_e32 v56, 0x70, v22
	v_mov_b32_e32 v57, v1
	v_ashrrev_i32_e32 v0, 1, v74
	s_movk_i32 s0, 0xffe0
	v_lshl_add_u64 v[10:11], v[10:11], 0, v[56:57]
	v_bfi_b32 v0, s0, v0, v74
	v_readlane_b32 s0, v253, 9
	global_load_dwordx4 v[10:13], v[10:11], off offset:1152
	v_readlane_b32 s1, v253, 10
	v_bfe_u32 v18, v16, 5, 2
	v_and_b32_e32 v19, 3, v75
	v_mov_b64_e32 v[14:15], s[0:1]
	v_mad_i64_i32 v[14:15], s[0:1], v0, s3, v[14:15]
	v_lshrrev_b32_e32 v0, 1, v74
	v_and_b32_e32 v0, 16, v0
	v_lshl_add_u64 v[14:15], v[14:15], 0, v[0:1]
	global_load_dwordx4 v[110:113], v[14:15], off offset:128
	global_load_dwordx4 v[106:109], v[14:15], off offset:160
	global_load_dwordx4 v[102:105], v[14:15], off offset:192
	global_load_dwordx4 v[98:101], v[14:15], off offset:224
	v_add_u32_e32 v84, 64, v155
	v_add_u32_e32 v88, 0x60, v155
	v_add_u32_e32 v92, 64, v72
	v_mad_i64_i32 v[84:85], s[0:1], v84, s3, v[50:51]
	v_mad_i64_i32 v[88:89], s[0:1], v88, s3, v[50:51]
	v_mad_i64_i32 v[92:93], s[0:1], v92, s3, v[50:51]
	v_lshl_add_u64 v[84:85], v[84:85], 0, v[52:53]
	v_lshl_add_u64 v[88:89], v[88:89], 0, v[52:53]
	v_lshl_add_u64 v[92:93], v[92:93], 0, v[56:57]
	global_load_dwordx4 v[84:87], v[84:85], off offset:2048
	global_load_dwordx4 v[88:91], v[88:89], off offset:2048
	global_load_dwordx4 v[92:95], v[92:93], off offset:1152
	v_and_b32_e32 v14, 0xfffff0, v75
	v_lshlrev_b32_e32 v15, 1, v75
	v_and_or_b32 v14, v15, 8, v14
	v_lshrrev_b32_e32 v15, 1, v75
	v_lshrrev_b32_e32 v14, 1, v14
	v_or_b32_e32 v14, v14, v18
	v_and_or_b32 v15, v15, 4, v19
	v_lshlrev_b32_e32 v14, 9, v14
	v_lshlrev_b32_e32 v15, 6, v15
	v_and_b32_e32 v19, 48, v22
	v_and_b32_e32 v20, 0xfffff0, v17
	v_lshlrev_b32_e32 v17, 1, v17
	v_or3_b32 v14, v14, v15, v19
	v_and_or_b32 v17, v17, 8, v20
	v_lshrrev_b32_e32 v17, 1, v17
	v_add_u32_e32 v212, 0, v14
	v_and_b32_e32 v76, 31, v74
	v_or_b32_e32 v17, v17, v18
	s_waitcnt vmcnt(0)
	v_lshlrev_b32_e32 v17, 9, v17
	v_lshlrev_b32_e32 v26, 7, v76
	v_and_b32_e32 v27, 0x70, v16
	v_or3_b32 v15, v17, v15, v19
	v_add_u32_e32 v213, 0, v15
	v_and_b32_e32 v77, 63, v74
	v_lshlrev_b32_e32 v28, 3, v77
	v_and_b32_e32 v22, 0xc0, v22
	v_and_or_b32 v29, v28, 24, v22
	v_lshlrev_b32_e32 v22, 1, v74
	v_and_b32_e32 v30, 32, v22
	v_mad_i64_i32 v[58:59], s[0:1], v155, s3, 0
	v_mad_i64_i32 v[54:55], s[0:1], v72, s3, 0
	s_mov_b32 s15, s13
	s_mov_b32 s1, s13
	s_mov_b32 s16, s13
	s_mov_b32 s17, s13
	s_mov_b32 s18, s13
	s_mov_b32 s19, s13
	s_mov_b32 s20, s13
	s_mov_b32 s21, s13
	s_mov_b32 s22, s13
	s_mov_b32 s23, s13
	s_mov_b32 s24, s13
	s_mov_b32 s25, s13
	s_mov_b32 s26, s13
	s_mov_b32 s27, s13
	v_add_u32_e32 v68, 64, v72
	v_mov_b32_e32 v209, 0
	s_waitcnt vmcnt(6)
	ds_write_b128 v212, v[2:5]
	v_lshlrev_b32_e32 v2, 7, v72
	v_and_b32_e32 v3, 0x70, v74
	v_bitop3_b32 v2, v56, v2, v3 bitop3:0xde
	v_add_u32_e32 v214, 0, v2
	v_bitop3_b32 v2, v0, v26, v27 bitop3:0xde
	v_add_u32_e32 v215, 0, v2
	s_waitcnt vmcnt(5)
	ds_write_b128 v213, v[6:9]
	v_add_u32_e32 v72, 0x80, v72
	s_waitcnt vmcnt(4)
	ds_write_b128 v214, v[10:13] offset:32768
	s_waitcnt lgkmcnt(0)
	s_barrier
; __device__ __forceinline__ void partialSM(f32x16& p0, f32x16& p1, float& m_reg, float& mn, float& alpha, float C, float thrRaw) {
;   float pmax = p0[0];
; #pragma unroll
;   for (int r = 1; r < 16; ++r) pmax = fmaxf(pmax, p0[r]);
; #pragma unroll
;   for (int r = 0; r < 16; ++r) pmax = fmaxf(pmax, p1[r]);
;   { auto rr = __builtin_amdgcn_permlane32_swap(__float_as_uint(pmax), __float_as_uint(pmax), false, false);
;     pmax = fmaxf(__uint_as_float(rr[0]), __uint_as_float(rr[1])); }
;   if (__builtin_expect(__all(pmax - m_reg <= thrRaw), 1)) { mn = m_reg; alpha = 1.f; }
;   else { mn = fmaxf(m_reg, pmax); alpha = __builtin_amdgcn_exp2f((m_reg - mn) * C); m_reg = mn; }
;   float mnC = -mn * C;
; #pragma unroll
;   for (int r = 0; r < 16; ++r) p0[r] = fmaf(p0[r], C, mnC);
; #pragma unroll
;   for (int r = 0; r < 16; ++r) p1[r] = fmaf(p1[r], C, mnC);
; #pragma unroll
;   for (int r = 0; r < 16; ++r) p0[r] = __builtin_amdgcn_exp2f(p0[r]);
; template <int DK, bool QL>
; __device__ __forceinline__ void qkt(f32x16& p0, f32x16& p1, const bf16* Ks, const bf16x8* qr, const char* ql, int r32, int hi) {
;   p0 = f32x16{}; p1 = f32x16{};
; #pragma unroll
;   for (int d0 = 0; d0 < DK / 16; ++d0) { int cb = (d0 * 16 + hi * 8) * 2;
;     const bf16x8 qv = QL ? *reinterpret_cast<const bf16x8*>(ql + d0 * 1024) : qr[d0];
;     bf16x8 b0 = *reinterpret_cast<const bf16x8*>((const char*)Ks + kswz<DK>(r32, cb));
;     bf16x8 b1 = *reinterpret_cast<const bf16x8*>((const char*)Ks + kswz<DK>(32 + r32, cb));
;     p0 = __builtin_amdgcn_mfma_f32_32x32x16_bf16(b0, qv, p0, 0, 0, 0);
;     p1 = __builtin_amdgcn_mfma_f32_32x32x16_bf16(b1, qv, p1, 0, 0, 0); }
	ds_read_b128 v[2:5], v215 offset:32768
	ds_read_b128 v[6:9], v215 offset:36864
	s_waitcnt vmcnt(3) lgkmcnt(1)
	v_mfma_f32_32x32x16_bf16 v[34:49], v[2:5], v[110:113], 0
	v_and_b32_e32 v2, 0x3fffffc0, v74
	v_lshl_add_u32 v207, v2, 2, s8
	v_or_b32_e32 v2, 32, v0
	v_bitop3_b32 v2, v2, v26, v27 bitop3:0xde
	v_add_u32_e32 v216, 0, v2
	ds_read_b128 v[18:21], v216 offset:32768
	ds_read_b128 v[22:25], v216 offset:36864
	s_waitcnt vmcnt(2) lgkmcnt(1)
	v_mfma_f32_32x32x16_bf16 v[34:49], v[18:21], v[106:109], v[34:49]
	v_and_b32_e32 v18, 0x100, v28
	v_or3_b32 v78, v29, v30, v18
	v_or_b32_e32 v18, 64, v0
	v_bitop3_b32 v18, v18, v26, v27 bitop3:0xde
	v_add_u32_e32 v217, 0, v18
	ds_read_b128 v[18:21], v217 offset:32768
	s_mov_b32 s8, 1
	v_mfma_f32_32x32x16_bf16 v[2:17], v[6:9], v[110:113], 0
	v_add_u32_e32 v211, s2, v78
	v_writelane_b32 v254, s0, 62
	v_lshl_add_u32 v208, v76, 2, v207
	s_nop 0
	v_writelane_b32 v255, s2, 0
	v_writelane_b32 v255, s3, 1
	v_writelane_b32 v255, s4, 2
	s_waitcnt lgkmcnt(1)
	v_mfma_f32_32x32x16_bf16 v[2:17], v[22:25], v[106:109], v[2:17]
	ds_read_b128 v[22:25], v217 offset:36864
	v_writelane_b32 v255, s5, 3
	v_writelane_b32 v255, s6, 4
	v_writelane_b32 v255, s7, 5
	v_writelane_b32 v255, s8, 6
	v_writelane_b32 v255, s9, 7
	v_writelane_b32 v255, s10, 8
	s_waitcnt vmcnt(1) lgkmcnt(1)
	v_mfma_f32_32x32x16_bf16 v[34:49], v[18:21], v[102:105], v[34:49]
	v_or_b32_e32 v18, 0x60, v0
	v_bitop3_b32 v18, v18, v26, v27 bitop3:0xde
	v_add_u32_e32 v218, 0, v18
	ds_read_b128 v[18:21], v218 offset:32768
	ds_read_b128 v[60:63], v218 offset:36864
	v_writelane_b32 v255, s11, 9
	v_writelane_b32 v255, s12, 10
	s_waitcnt lgkmcnt(2)
	v_mfma_f32_32x32x16_bf16 v[2:17], v[22:25], v[102:105], v[2:17]
	v_writelane_b32 v255, s13, 11
	v_writelane_b32 v255, s14, 12
	v_writelane_b32 v254, s1, 63
	v_writelane_b32 v255, s15, 13
	v_mad_i64_i32 v[68:69], s[0:1], v68, s3, v[50:51]
	v_lshl_add_u64 v[68:69], v[68:69], 0, v[56:57]
	s_waitcnt vmcnt(0) lgkmcnt(1)
	v_mfma_f32_32x32x16_bf16 v[34:49], v[18:21], v[98:101], v[34:49]
	v_mov_b64_e32 v[32:33], s[26:27]
	v_mov_b64_e32 v[18:19], s[12:13]
	v_mov_b64_e32 v[30:31], s[24:25]
	v_mov_b64_e32 v[28:29], s[22:23]
	v_mov_b64_e32 v[26:27], s[20:21]
	v_mov_b64_e32 v[24:25], s[18:19]
	v_mov_b64_e32 v[22:23], s[16:17]
	s_waitcnt lgkmcnt(0)
	v_mfma_f32_32x32x16_bf16 v[2:17], v[60:63], v[98:101], v[2:17]
	s_nop 2
	v_max_f32_e32 v60, v35, v35
	v_max_f32_e32 v61, v34, v34
	v_max_f32_e32 v60, v61, v60
	v_max3_f32 v60, v60, v36, v37
	v_max3_f32 v60, v60, v38, v39
	v_max3_f32 v60, v60, v40, v41
	v_max3_f32 v60, v60, v42, v43
	v_max3_f32 v60, v60, v44, v45
	v_max3_f32 v60, v60, v46, v47
	v_max3_f32 v60, v60, v48, v49
	v_max3_f32 v60, v60, v2, v3
	v_max3_f32 v60, v60, v4, v5
	v_max3_f32 v60, v60, v6, v7
	v_max3_f32 v60, v60, v8, v9
	v_max3_f32 v73, v60, v10, v11
	v_max3_f32 v73, v73, v12, v13
	v_add_u32_e32 v60, 64, v75
	v_add_u32_e32 v62, 0x60, v75
	v_max3_f32 v73, v73, v14, v15
	v_mad_i64_i32 v[60:61], s[0:1], v60, s3, v[50:51]
	v_mad_i64_i32 v[62:63], s[0:1], v62, s3, v[50:51]
	v_max3_f32 v79, v73, v16, v17
	v_mad_i64_i32 v[72:73], s[0:1], v72, s3, v[50:51]
	v_lshl_add_u64 v[60:61], v[60:61], 0, v[52:53]
	v_lshl_add_u64 v[64:65], v[62:63], 0, v[52:53]
	v_lshl_add_u64 v[56:57], v[72:73], 0, v[56:57]
	s_nop 0
	v_add_u32_e32 v72, 0x80, v155
	v_mov_b64_e32 v[20:21], s[14:15]
	global_load_dwordx4 v[122:125], v[56:57], off offset:1152
	v_add_u32_e32 v56, 0xa0, v155
	v_mad_i64_i32 v[56:57], s[0:1], v56, s3, v[50:51]
	v_lshl_add_u64 v[56:57], v[56:57], 0, v[52:53]
	v_mad_i64_i32 v[50:51], s[0:1], v72, s3, v[50:51]
	v_lshl_add_u64 v[50:51], v[50:51], 0, v[52:53]
	global_load_dwordx4 v[118:121], v[56:57], off offset:2048
	global_load_dwordx4 v[114:117], v[50:51], off offset:2048
	v_mov_b32_e32 v50, v79
	s_nop 1
	v_permlane32_swap_b32_e32 v79, v50
	v_max_f32_e32 v50, v50, v50
	v_max_f32_e32 v51, v79, v79
	v_max_f32_e32 v50, v51, v50
	v_add_f32_e32 v51, 0x7149f2ca, v50
	s_mov_b32 s0, 0x42800000
	v_max_f32_e32 v50, 0xf149f2ca, v50
	v_cmp_ge_f32_e32 vcc, s0, v51
	v_sub_f32_e32 v51, 0xf149f2ca, v50
	v_mul_f32_e32 v51, 0x3e38aa3b, v51
	v_exp_f32_e32 v51, v51
	s_cmp_eq_u64 vcc, exec
	s_cselect_b64 vcc, -1, 0
	v_cndmask_b32_e32 v142, v50, v199, vcc
	v_mul_f32_e32 v50, 0xbe38aa3b, v142
	v_cndmask_b32_e64 v219, v51, 1.0, vcc
	v_mov_b32_e32 v51, v50
	v_fmac_f32_e32 v51, 0x3e38aa3b, v49
	s_mov_b32 s0, 0x3e38aa3b
	v_fmamk_f32 v34, v34, 0x3e38aa3b, v50
	v_fmamk_f32 v35, v35, 0x3e38aa3b, v50
	v_fmamk_f32 v36, v36, 0x3e38aa3b, v50
	v_fmamk_f32 v37, v37, 0x3e38aa3b, v50
	v_fmamk_f32 v38, v38, 0x3e38aa3b, v50
	v_fmamk_f32 v39, v39, 0x3e38aa3b, v50
	v_fmamk_f32 v40, v40, 0x3e38aa3b, v50
	v_fmamk_f32 v41, v41, 0x3e38aa3b, v50
	v_fmamk_f32 v42, v42, 0x3e38aa3b, v50
	v_fmamk_f32 v43, v43, 0x3e38aa3b, v50
	v_fmamk_f32 v44, v44, 0x3e38aa3b, v50
	v_fmamk_f32 v45, v45, 0x3e38aa3b, v50
	v_fmamk_f32 v46, v46, 0x3e38aa3b, v50
	v_fmamk_f32 v47, v47, 0x3e38aa3b, v50
	v_fmamk_f32 v48, v48, 0x3e38aa3b, v50
	v_pk_fma_f32 v[138:139], v[2:3], s[0:1], v[50:51] op_sel_hi:[1,0,0]
	s_addk_i32 s2, 0x4000
	v_and_b32_e32 v2, 15, v74
	v_exp_f32_e32 v177, v34
	v_exp_f32_e32 v226, v35
	v_exp_f32_e32 v161, v36
	v_exp_f32_e32 v223, v37
	v_exp_f32_e32 v153, v38
	v_exp_f32_e32 v176, v39
	v_exp_f32_e32 v152, v40
	v_exp_f32_e32 v160, v41
	v_exp_f32_e32 v149, v42
	v_exp_f32_e32 v151, v43
	v_exp_f32_e32 v147, v44
	v_exp_f32_e32 v150, v45
	v_exp_f32_e32 v145, v46
	v_exp_f32_e32 v148, v47
	v_exp_f32_e32 v144, v48
	v_exp_f32_e32 v146, v51
	v_add_u32_e32 v210, s2, v78
	v_lshl_or_b32 v58, v2, 4, v58
	v_readlane_b32 s2, v254, 34
	v_and_b32_e32 v2, 7, v74
	s_waitcnt vmcnt(3)
; #define SBAR() __builtin_amdgcn_sched_barrier(0)
; #define SLOAD(i, k0) do { sr_[i].vs0 = *reinterpret_cast<const bf16x8*>(&Vh[(long)((k0) + sr) * LDP + sc]); sr_[i].vs1 = *reinterpret_cast<const bf16x8*>(&Vh[(long)((k0) + 32 + sr) * LDP + sc]); \
;     sr_[i].ks0 = *reinterpret_cast<const bf16x8*>(&Kh[(long)((k0) + ksr) * LDP + ksc]); if (DK == 128) sr_[i].ks1 = *reinterpret_cast<const bf16x8*>(&Kh[(long)((k0) + 32 + ksr) * LDP + ksc]); } while (0)
; #define HOOK(P0, P1, j) do { if (NA) na_hook(P0, P1, krow0 + (j), q_row, q_col, win_r, win_c, rpb, inv_scale, hi); } while (0)
; __device__ __forceinline__ void finishSM(f32x16& p0, f32x16& p1, float alpha, float& l_reg, bf16x8& pa0, bf16x8& pa1, bf16x8& pa2, bf16x8& pa3) {
; #pragma unroll
;   for (int r = 0; r < 16; ++r) p1[r] = __builtin_amdgcn_exp2f(p1[r]);
;   float ps = 0;
; #pragma unroll
;   for (int r = 0; r < 16; ++r) ps += p0[r];
; #pragma unroll
;   for (int r = 0; r < 16; ++r) ps += p1[r];
;   { auto rr = __builtin_amdgcn_permlane32_swap(__float_as_uint(ps), __float_as_uint(ps), false, false);
;     ps = __uint_as_float(rr[0]) + __uint_as_float(rr[1]); }
;   l_reg = l_reg * alpha + ps;
;     ...
;   PK4(p0, 0, pa0); PK4(p0, 8, pa1); PK4(p1, 0, pa2); PK4(p1, 8, pa3);
; template <int DK, bool NA, bool QL, int SD> ...
;     ...
;   for (int j = 1; j + 1 < NT; j += 2) {
;     SBAR(); qkt<DK, QL>(pB0, pB1, (bf16*)((char*)K_lds + SHM_K), qr, ql, r32, hi); HOOK(pB0, pB1, j);
;     finishSM(pA0, pA1, alA, l_reg, pa0, pa1, pa2, pa3); SBAR();
;     SLOAD(SO, (j + SD) * KVBLK); SBAR();
	v_readlane_b32 s3, v254, 35
	v_lshl_or_b32 v54, v2, 4, v54
	v_pk_fma_f32 v[132:133], v[16:17], s[0:1], v[50:51] op_sel_hi:[1,0,0]
	v_pk_fma_f32 v[134:135], v[14:15], s[0:1], v[50:51] op_sel_hi:[1,0,0]
	v_pk_fma_f32 v[140:141], v[12:13], s[0:1], v[50:51] op_sel_hi:[1,0,0]
	v_pk_fma_f32 v[126:127], v[10:11], s[0:1], v[50:51] op_sel_hi:[1,0,0]
	v_pk_fma_f32 v[128:129], v[8:9], s[0:1], v[50:51] op_sel_hi:[1,0,0]
	v_pk_fma_f32 v[130:131], v[6:7], s[0:1], v[50:51] op_sel_hi:[1,0,0]
	v_pk_fma_f32 v[136:137], v[4:5], s[0:1], v[50:51] op_sel_hi:[1,0,0]
	s_waitcnt vmcnt(5)
	ds_write_b128 v212, v[84:87] offset:16384
	s_waitcnt vmcnt(4)
	ds_write_b128 v213, v[88:91] offset:16384
	s_waitcnt vmcnt(3)
	ds_write_b128 v214, v[92:95] offset:49152
	v_lshl_add_u64 v[156:157], s[2:3], 0, v[58:59]
	v_lshl_add_u64 v[158:159], s[2:3], 0, v[54:55]
	v_mov_b64_e32 v[48:49], v[32:33]
	v_mov_b64_e32 v[64:65], v[32:33]
	v_mov_b64_e32 v[2:3], v[18:19]
	v_cmp_gt_u32_e64 s[0:1], 32, v77
	v_mov_b64_e32 v[46:47], v[30:31]
	v_mov_b64_e32 v[44:45], v[28:29]
	v_mov_b64_e32 v[42:43], v[26:27]
	v_mov_b64_e32 v[40:41], v[24:25]
	v_mov_b64_e32 v[38:39], v[22:23]
	v_mov_b64_e32 v[36:37], v[20:21]
	v_mov_b64_e32 v[34:35], v[18:19]
	v_mov_b64_e32 v[62:63], v[30:31]
	v_mov_b64_e32 v[60:61], v[28:29]
	v_mov_b64_e32 v[58:59], v[26:27]
	v_mov_b64_e32 v[56:57], v[24:25]
	v_mov_b64_e32 v[54:55], v[22:23]
	v_mov_b64_e32 v[52:53], v[20:21]
	v_mov_b64_e32 v[50:51], v[18:19]
	v_mov_b64_e32 v[4:5], v[20:21]
	v_mov_b64_e32 v[6:7], v[22:23]
	v_mov_b64_e32 v[8:9], v[24:25]
	v_mov_b64_e32 v[10:11], v[26:27]
	v_mov_b64_e32 v[12:13], v[28:29]
	v_mov_b64_e32 v[14:15], v[30:31]
	v_mov_b64_e32 v[16:17], v[32:33]
	v_readlane_b32 s6, v254, 32
	v_readlane_b32 s7, v254, 33
	s_nop 3
	v_lshl_add_u64 v[178:179], v[156:157], 0, s[6:7]
	v_lshl_add_u64 v[204:205], v[158:159], 0, s[6:7]
	s_mov_b32 s6, 0xe130000
	s_mov_b32 s7, 0
	s_nop 0
	v_lshl_add_u64 v[180:181], v[178:179], 0, s[6:7]
	s_mov_b32 s6, 0xe0e0000
	s_nop 0
	v_lshl_add_u64 v[178:179], v[178:179], 0, s[6:7]
	v_lshl_add_u64 v[204:205], v[204:205], 0, s[6:7]
	s_waitcnt lgkmcnt(0)
	s_barrier
.LBB0_701:
	ds_read_b128 v[66:69], v215 offset:49152
	ds_read_b128 v[70:73], v215 offset:53248
	v_exp_f32_e32 v143, v138
	v_add_f32_e32 v138, v226, v177
	s_waitcnt lgkmcnt(1)
	v_mfma_f32_32x32x16_bf16 v[82:97], v[66:69], v[110:113], 0
	v_add_f32_e32 v138, v161, v138
	v_add_f32_e32 v138, v223, v138
	v_add_f32_e32 v138, v153, v138
	ds_read_b128 v[228:231], v216 offset:49152
	ds_read_b128 v[232:235], v216 offset:53248
	v_add_f32_e32 v138, v176, v138
	v_add_f32_e32 v138, v152, v138
	v_add_f32_e32 v138, v160, v138
	s_waitcnt lgkmcnt(2)
	v_mfma_f32_32x32x16_bf16 v[66:81], v[70:73], v[110:113], 0
	v_add_f32_e32 v138, v149, v138
	v_add_f32_e32 v138, v151, v138
	v_add_f32_e32 v138, v147, v138
	v_add_f32_e32 v138, v150, v138
	v_add_f32_e32 v138, v145, v138
	v_exp_f32_e32 v164, v139
	v_add_f32_e32 v138, v148, v138
	s_waitcnt lgkmcnt(1)
	v_mfma_f32_32x32x16_bf16 v[82:97], v[228:231], v[106:109], v[82:97]
	v_exp_f32_e32 v136, v136
	v_add_f32_e32 v138, v144, v138
	v_exp_f32_e32 v137, v137
	v_add_f32_e32 v138, v146, v138
	v_exp_f32_e32 v130, v130
	v_add_f32_e32 v138, v143, v138
	v_exp_f32_e32 v131, v131
	s_waitcnt lgkmcnt(0)
	v_mfma_f32_32x32x16_bf16 v[66:81], v[232:235], v[106:109], v[66:81]
	ds_read_b128 v[228:231], v217 offset:49152
	ds_read_b128 v[232:235], v217 offset:53248
	v_add_f32_e32 v138, v164, v138
	v_exp_f32_e32 v128, v128
	v_add_f32_e32 v138, v136, v138
	v_exp_f32_e32 v129, v129
	v_add_f32_e32 v138, v137, v138
	v_exp_f32_e32 v126, v126
	s_waitcnt lgkmcnt(1)
	v_mfma_f32_32x32x16_bf16 v[82:97], v[228:231], v[102:105], v[82:97]
	v_add_f32_e32 v138, v130, v138
	v_exp_f32_e32 v127, v127
	v_add_f32_e32 v138, v131, v138
	v_exp_f32_e32 v165, v140
	v_add_f32_e32 v138, v128, v138
	v_exp_f32_e32 v166, v141
	v_add_f32_e32 v138, v129, v138
	s_waitcnt lgkmcnt(0)
	v_mfma_f32_32x32x16_bf16 v[66:81], v[232:235], v[102:105], v[66:81]
	ds_read_b128 v[228:231], v218 offset:49152
	ds_read_b128 v[232:235], v218 offset:53248
	v_exp_f32_e32 v134, v134
	v_add_f32_e32 v138, v126, v138
	v_exp_f32_e32 v135, v135
	v_add_f32_e32 v138, v127, v138
	v_exp_f32_e32 v132, v132
	v_add_f32_e32 v138, v165, v138
	s_waitcnt lgkmcnt(1)
	v_mfma_f32_32x32x16_bf16 v[82:97], v[228:231], v[98:101], v[82:97]
	v_exp_f32_e32 v133, v133
	v_add_f32_e32 v138, v166, v138
	v_add_f32_e32 v138, v134, v138
	v_add_f32_e32 v138, v135, v138
	v_add_f32_e32 v138, v132, v138
	v_add_f32_e32 v220, v133, v138
	v_mov_b32_e32 v221, v220
	s_waitcnt lgkmcnt(0)
	v_mfma_f32_32x32x16_bf16 v[66:81], v[232:235], v[98:101], v[66:81]
	v_cvt_pk_bf16_f32 v138, v177, v226
	v_cvt_pk_bf16_f32 v139, v161, v223
	v_cvt_pk_bf16_f32 v140, v153, v176
	v_cvt_pk_bf16_f32 v141, v152, v160
	v_cvt_pk_bf16_f32 v222, v149, v151
	v_cvt_pk_bf16_f32 v223, v147, v150
	v_cvt_pk_bf16_f32 v224, v145, v148
	v_permlane32_swap_b32_e32 v220, v221
	v_cvt_pk_bf16_f32 v225, v144, v146
	v_cvt_pk_bf16_f32 v144, v143, v164
	v_cvt_pk_bf16_f32 v145, v136, v137
	v_cvt_pk_bf16_f32 v146, v130, v131
	v_cvt_pk_bf16_f32 v147, v128, v129
	v_cvt_pk_bf16_f32 v148, v126, v127
	v_cvt_pk_bf16_f32 v149, v165, v166
	v_cvt_pk_bf16_f32 v150, v134, v135
	v_cvt_pk_bf16_f32 v151, v132, v133
	global_load_dwordx4 v[182:185], v[178:179], off offset:2048
	global_load_dwordx4 v[194:197], v[180:181], off offset:2048
	global_load_dwordx4 v[134:137], v[204:205], off offset:1152
	s_mov_b32 s4, 0xa0000
	s_mov_b32 s5, 0
	s_nop 0
	v_lshl_add_u64 v[178:179], v[178:179], 0, s[4:5]
	v_lshl_add_u64 v[180:181], v[180:181], 0, s[4:5]
	v_lshl_add_u64 v[204:205], v[204:205], 0, s[4:5]
	ds_read_b64_tr_b16 v[226:227], v211 offset:0
	ds_read_b64_tr_b16 v[228:229], v211 offset:0x800
	ds_read_b64_tr_b16 v[230:231], v211 offset:0x1000
	ds_read_b64_tr_b16 v[232:233], v211 offset:0x1800
	ds_read_b64_tr_b16 v[234:235], v211 offset:0x2000
	ds_read_b64_tr_b16 v[236:237], v211 offset:0x2800
	ds_read_b64_tr_b16 v[238:239], v211 offset:0x3000
	ds_read_b64_tr_b16 v[240:241], v211 offset:0x3800
	s_waitcnt lgkmcnt(4)
; #define SBAR() __builtin_amdgcn_sched_barrier(0)
; __device__ __forceinline__ void partialSM(f32x16& p0, f32x16& p1, float& m_reg, float& mn, float& alpha, float C, float thrRaw) {
;   float pmax = p0[0];
; #pragma unroll
;   for (int r = 1; r < 16; ++r) pmax = fmaxf(pmax, p0[r]);
; #pragma unroll
;   for (int r = 0; r < 16; ++r) pmax = fmaxf(pmax, p1[r]);
;   { auto rr = __builtin_amdgcn_permlane32_swap(__float_as_uint(pmax), __float_as_uint(pmax), false, false);
;     pmax = fmaxf(__uint_as_float(rr[0]), __uint_as_float(rr[1])); }
;   if (__builtin_expect(__all(pmax - m_reg <= thrRaw), 1)) { mn = m_reg; alpha = 1.f; }
;   else { mn = fmaxf(m_reg, pmax); alpha = __builtin_amdgcn_exp2f((m_reg - mn) * C); m_reg = mn; }
; template <int D0> __device__ __forceinline__ void pv_one(f32x16& od, int vb, bf16x8 pa0, bf16x8 pa1, bf16x8 pa2, bf16x8 pa3) {
;   const s16x4 l0 = tr_read<v_rd_off(D0, 0, 0)>(vb), h0 = tr_read<v_rd_off(D0, 0, 1)>(vb), l1 = tr_read<v_rd_off(D0, 1, 0)>(vb), h1 = tr_read<v_rd_off(D0, 1, 1)>(vb);
;   const s16x4 l2 = tr_read<v_rd_off(D0, 2, 0)>(vb), h2 = tr_read<v_rd_off(D0, 2, 1)>(vb), l3 = tr_read<v_rd_off(D0, 3, 0)>(vb), h3 = tr_read<v_rd_off(D0, 3, 1)>(vb);
;   asm volatile("s_waitcnt lgkmcnt(0)" ::: "memory"); SBAR();
;     ...
;   od = __builtin_amdgcn_mfma_f32_32x32x16_bf16(pa0, PK(l0, h0), od, 0, 0, 0);
;   od = __builtin_amdgcn_mfma_f32_32x32x16_bf16(pa1, PK(l1, h1), od, 0, 0, 0);
;   od = __builtin_amdgcn_mfma_f32_32x32x16_bf16(pa2, PK(l2, h2), od, 0, 0, 0);
;   od = __builtin_amdgcn_mfma_f32_32x32x16_bf16(pa3, PK(l3, h3), od, 0, 0, 0);
;     ...
; }
; __device__ __forceinline__ void pv_d0(f32x16* o, int vb, bf16x8 pa0, bf16x8 pa1, bf16x8 pa2, bf16x8 pa3) {
;   pv_one<0>(o[0], vb, pa0, pa1, pa2, pa3); pv_one<1>(o[1], vb, pa0, pa1, pa2, pa3); pv_one<2>(o[2], vb, pa0, pa1, pa2, pa3); pv_one<3>(o[3], vb, pa0, pa1, pa2, pa3);
	s_nop 0
	v_mfma_f32_32x32x16_bf16 v[2:17], v[138:141], v[226:229], v[2:17]
	ds_read_b64_tr_b16 v[226:227], v211 offset:0x200
	ds_read_b64_tr_b16 v[228:229], v211 offset:0xa00
	v_mfma_f32_32x32x16_bf16 v[2:17], v[222:225], v[230:233], v[2:17]
	ds_read_b64_tr_b16 v[230:231], v211 offset:0x1200
	ds_read_b64_tr_b16 v[232:233], v211 offset:0x1a00
	s_waitcnt lgkmcnt(4)
	v_mfma_f32_32x32x16_bf16 v[2:17], v[144:147], v[234:237], v[2:17]
	ds_read_b64_tr_b16 v[234:235], v211 offset:0x2200
	ds_read_b64_tr_b16 v[236:237], v211 offset:0x2a00
	v_mfma_f32_32x32x16_bf16 v[2:17], v[148:151], v[238:241], v[2:17]
	ds_read_b64_tr_b16 v[238:239], v211 offset:0x3200
	ds_read_b64_tr_b16 v[240:241], v211 offset:0x3a00
	s_waitcnt lgkmcnt(4)
	v_mfma_f32_32x32x16_bf16 v[50:65], v[138:141], v[226:229], v[50:65]
	ds_read_b64_tr_b16 v[226:227], v211 offset:0x400
	ds_read_b64_tr_b16 v[228:229], v211 offset:0xc00
	v_mfma_f32_32x32x16_bf16 v[50:65], v[222:225], v[230:233], v[50:65]
	ds_read_b64_tr_b16 v[230:231], v211 offset:0x1400
	ds_read_b64_tr_b16 v[232:233], v211 offset:0x1c00
	s_waitcnt lgkmcnt(4)
	v_mfma_f32_32x32x16_bf16 v[50:65], v[144:147], v[234:237], v[50:65]
	ds_read_b64_tr_b16 v[234:235], v211 offset:0x2400
	ds_read_b64_tr_b16 v[236:237], v211 offset:0x2c00
	v_mfma_f32_32x32x16_bf16 v[50:65], v[148:151], v[238:241], v[50:65]
	ds_read_b64_tr_b16 v[238:239], v211 offset:0x3400
	ds_read_b64_tr_b16 v[240:241], v211 offset:0x3c00
	s_waitcnt lgkmcnt(4)
	v_mfma_f32_32x32x16_bf16 v[34:49], v[138:141], v[226:229], v[34:49]
	ds_read_b64_tr_b16 v[226:227], v211 offset:0x600
	ds_read_b64_tr_b16 v[228:229], v211 offset:0xe00
	v_mfma_f32_32x32x16_bf16 v[34:49], v[222:225], v[230:233], v[34:49]
	ds_read_b64_tr_b16 v[230:231], v211 offset:0x1600
	ds_read_b64_tr_b16 v[232:233], v211 offset:0x1e00
	s_waitcnt lgkmcnt(4)
	v_mfma_f32_32x32x16_bf16 v[34:49], v[144:147], v[234:237], v[34:49]
	ds_read_b64_tr_b16 v[234:235], v211 offset:0x2600
	ds_read_b64_tr_b16 v[236:237], v211 offset:0x2e00
	v_mfma_f32_32x32x16_bf16 v[34:49], v[148:151], v[238:241], v[34:49]
	ds_read_b64_tr_b16 v[238:239], v211 offset:0x3600
	ds_read_b64_tr_b16 v[240:241], v211 offset:0x3e00
	s_waitcnt lgkmcnt(6)
	v_mfma_f32_32x32x16_bf16 v[18:33], v[138:141], v[226:229], v[18:33]
	v_max_f32_e32 v138, v83, v82
	v_max3_f32 v138, v138, v84, v85
	v_max3_f32 v138, v138, v86, v87
	v_max3_f32 v138, v138, v88, v89
	v_max3_f32 v138, v138, v90, v91
	v_max3_f32 v138, v138, v92, v93
	v_max3_f32 v138, v138, v94, v95
	s_waitcnt lgkmcnt(4)
	v_mfma_f32_32x32x16_bf16 v[18:33], v[222:225], v[230:233], v[18:33]
	v_max3_f32 v138, v138, v96, v97
	v_max3_f32 v138, v138, v66, v67
	v_max3_f32 v138, v138, v68, v69
	v_max3_f32 v138, v138, v70, v71
	v_max3_f32 v138, v138, v72, v73
	v_max3_f32 v138, v138, v74, v75
	v_max3_f32 v138, v138, v76, v77
	v_max3_f32 v138, v138, v78, v79
	s_waitcnt lgkmcnt(2)
	v_mfma_f32_32x32x16_bf16 v[18:33], v[144:147], v[234:237], v[18:33]
	v_max3_f32 v138, v138, v80, v81
	v_mov_b32_e32 v139, v138
	s_nop 1
	v_permlane32_swap_b32_e32 v138, v139
	v_max_f32_e32 v138, v139, v138
	v_sub_f32_e32 v139, v138, v142
	s_mov_b32 s2, 0x42800000
	v_cmp_ge_f32_e32 vcc, s2, v139
	v_max_f32_e32 v138, v142, v138
	s_waitcnt lgkmcnt(0)
	v_mfma_f32_32x32x16_bf16 v[18:33], v[148:151], v[238:241], v[18:33]
	v_sub_f32_e32 v139, v142, v138
	v_mul_f32_e32 v139, 0x3e38aa3b, v139
	v_exp_f32_e32 v139, v139
	s_cmp_eq_u64 vcc, exec
	s_cselect_b64 s[2:3], -1, 0
	s_waitcnt vmcnt(3)
	v_cndmask_b32_e64 v222, v139, 1.0, s[2:3]
	v_cmp_gt_f32_e32 vcc, 1.0, v222
	ds_write_b128 v214, v[122:125] offset:32768
	s_cbranch_vccz .LBB0_705
	s_and_saveexec_b64 s[4:5], s[0:1]
	ds_write_b32 v208, v222 offset:128
	s_or_b64 exec, exec, s[4:5]
	s_waitcnt lgkmcnt(0)
	v_add_u32_e32 v139, v207, v0
	ds_read_b128 v[144:147], v139 offset:224
	ds_read_b128 v[148:151], v139 offset:192
	ds_read_b128 v[224:227], v139 offset:160
	ds_read_b128 v[228:231], v139 offset:128
	s_waitcnt lgkmcnt(3)
	v_pk_mul_f32 v[14:15], v[14:15], v[144:145]
	s_waitcnt lgkmcnt(2)
	v_pk_mul_f32 v[10:11], v[10:11], v[148:149]
	s_waitcnt lgkmcnt(1)
	v_pk_mul_f32 v[6:7], v[6:7], v[224:225]
	v_pk_mul_f32 v[16:17], v[16:17], v[146:147]
	v_pk_mul_f32 v[12:13], v[12:13], v[150:151]
	v_pk_mul_f32 v[8:9], v[8:9], v[226:227]
	s_waitcnt lgkmcnt(0)
	v_pk_mul_f32 v[4:5], v[4:5], v[230:231]
	v_pk_mul_f32 v[2:3], v[2:3], v[228:229]
	v_pk_mul_f32 v[62:63], v[144:145], v[62:63]
	v_pk_mul_f32 v[58:59], v[148:149], v[58:59]
	v_pk_mul_f32 v[54:55], v[224:225], v[54:55]
	v_pk_mul_f32 v[64:65], v[146:147], v[64:65]
	v_pk_mul_f32 v[60:61], v[150:151], v[60:61]
	v_pk_mul_f32 v[56:57], v[226:227], v[56:57]
	v_pk_mul_f32 v[52:53], v[230:231], v[52:53]
	v_pk_mul_f32 v[50:51], v[228:229], v[50:51]
	v_pk_mul_f32 v[46:47], v[144:145], v[46:47]
	v_pk_mul_f32 v[42:43], v[148:149], v[42:43]
	v_pk_mul_f32 v[38:39], v[224:225], v[38:39]
	v_pk_mul_f32 v[48:49], v[146:147], v[48:49]
	v_pk_mul_f32 v[44:45], v[150:151], v[44:45]
	v_pk_mul_f32 v[40:41], v[226:227], v[40:41]
	v_pk_mul_f32 v[36:37], v[230:231], v[36:37]
	v_pk_mul_f32 v[34:35], v[228:229], v[34:35]
	v_pk_mul_f32 v[30:31], v[144:145], v[30:31]
	v_pk_mul_f32 v[26:27], v[148:149], v[26:27]
	v_pk_mul_f32 v[22:23], v[224:225], v[22:23]
	v_pk_mul_f32 v[32:33], v[146:147], v[32:33]
	v_pk_mul_f32 v[28:29], v[150:151], v[28:29]
	v_pk_mul_f32 v[24:25], v[226:227], v[24:25]
	v_pk_mul_f32 v[20:21], v[230:231], v[20:21]
	v_pk_mul_f32 v[18:19], v[228:229], v[18:19]
; #define SBAR() __builtin_amdgcn_sched_barrier(0)
; #define SLOAD(i, k0) do { sr_[i].vs0 = *reinterpret_cast<const bf16x8*>(&Vh[(long)((k0) + sr) * LDP + sc]); sr_[i].vs1 = *reinterpret_cast<const bf16x8*>(&Vh[(long)((k0) + 32 + sr) * LDP + sc]); \
;     sr_[i].ks0 = *reinterpret_cast<const bf16x8*>(&Kh[(long)((k0) + ksr) * LDP + ksc]); if (DK == 128) sr_[i].ks1 = *reinterpret_cast<const bf16x8*>(&Kh[(long)((k0) + 32 + ksr) * LDP + ksc]); } while (0)
; #define SWAIT() do { if (SD == 1) asm volatile("s_waitcnt vmcnt(0)" ::: "memory"); else if (DK == 128) asm volatile("s_waitcnt vmcnt(4)" ::: "memory"); else asm volatile("s_waitcnt vmcnt(3)" ::: "memory"); } while (0)
; #define RESC(a) do { if (__any((a) < 1.f)) { if (hi == 0) al_l[r32] = (a); asm volatile("s_waitcnt lgkmcnt(0)" ::: "memory"); \
;     _Pragma("unroll") for (int d = 0; d < 4; ++d) _Pragma("unroll") for (int r = 0; r < 16; ++r) o[d][r] *= al_l[crow(r, hi)]; } } while (0)
; __device__ __forceinline__ void partialSM(f32x16& p0, f32x16& p1, float& m_reg, float& mn, float& alpha, float C, float thrRaw) {
;     ...
;   for (int r = 0; r < 16; ++r) p0[r] = fmaf(p0[r], C, mnC);
; #pragma unroll
;   for (int r = 0; r < 16; ++r) p1[r] = fmaf(p1[r], C, mnC);
; #pragma unroll
;   for (int r = 0; r < 16; ++r) p0[r] = __builtin_amdgcn_exp2f(p0[r]);
; }
; __device__ __forceinline__ void finishSM(f32x16& p0, f32x16& p1, float alpha, float& l_reg, bf16x8& pa0, bf16x8& pa1, bf16x8& pa2, bf16x8& pa3) {
; #pragma unroll
;   for (int r = 0; r < 16; ++r) p1[r] = __builtin_amdgcn_exp2f(p1[r]);
;   float ps = 0;
; #pragma unroll
;   for (int r = 0; r < 16; ++r) ps += p0[r];
; #pragma unroll
;   for (int r = 0; r < 16; ++r) ps += p1[r];
;   { auto rr = __builtin_amdgcn_permlane32_swap(__float_as_uint(ps), __float_as_uint(ps), false, false);
;     ps = __uint_as_float(rr[0]) + __uint_as_float(rr[1]); }
;   l_reg = l_reg * alpha + ps;
;     ...
;   PK4(p0, 0, pa0); PK4(p0, 8, pa1); PK4(p1, 0, pa2); PK4(p1, 8, pa3);
; template <int DK, bool NA, bool QL, int SD> ...
;     ...
;     __syncthreads(); SWAIT(); SWRITE(0, SE);
;     RESC(alB); __syncthreads();
;     SBAR(); qkt<DK, QL>(pA0, pA1, K_lds, qr, ql, r32, hi); HOOK(pA0, pA1, j + 1);
;     finishSM(pB0, pB1, alB, l_reg, pa0, pa1, pa2, pa3); SBAR();
;     if (SD == 1 || j + 3 < NT) SLOAD(SE, (j + 1 + SD) * KVBLK); SBAR();
.LBB0_705:
	v_cndmask_b32_e64 v223, v138, v142, s[2:3]
	v_mul_f32_e32 v224, 0xbe38aa3b, v223
	s_mov_b32 s2, 0x3e38aa3b
	v_pk_fma_f32 v[82:83], v[82:83], s[2:3], v[224:225] op_sel_hi:[1,0,0]
	v_pk_fma_f32 v[84:85], v[84:85], s[2:3], v[224:225] op_sel_hi:[1,0,0]
	v_pk_fma_f32 v[86:87], v[86:87], s[2:3], v[224:225] op_sel_hi:[1,0,0]
	v_pk_fma_f32 v[88:89], v[88:89], s[2:3], v[224:225] op_sel_hi:[1,0,0]
	v_pk_fma_f32 v[90:91], v[90:91], s[2:3], v[224:225] op_sel_hi:[1,0,0]
	v_pk_fma_f32 v[92:93], v[92:93], s[2:3], v[224:225] op_sel_hi:[1,0,0]
	v_pk_fma_f32 v[94:95], v[94:95], s[2:3], v[224:225] op_sel_hi:[1,0,0]
	v_pk_fma_f32 v[96:97], v[96:97], s[2:3], v[224:225] op_sel_hi:[1,0,0]
	v_exp_f32_e32 v138, v82
	v_exp_f32_e32 v153, v83
	v_exp_f32_e32 v139, v84
	v_exp_f32_e32 v152, v85
	v_exp_f32_e32 v140, v86
	v_exp_f32_e32 v151, v87
	v_exp_f32_e32 v141, v88
	v_exp_f32_e32 v150, v89
	v_exp_f32_e32 v142, v90
	v_exp_f32_e32 v149, v91
	v_exp_f32_e32 v143, v92
	v_exp_f32_e32 v148, v93
	v_exp_f32_e32 v144, v94
	v_exp_f32_e32 v147, v95
	v_exp_f32_e32 v145, v96
	v_exp_f32_e32 v146, v97
	v_fmamk_f32 v233, v66, 0x3e38aa3b, v224
	v_fmamk_f32 v234, v67, 0x3e38aa3b, v224
	v_fmamk_f32 v235, v68, 0x3e38aa3b, v224
	v_fmamk_f32 v236, v69, 0x3e38aa3b, v224
	v_fmamk_f32 v237, v70, 0x3e38aa3b, v224
	v_fmamk_f32 v226, v71, 0x3e38aa3b, v224
	v_fmamk_f32 v227, v72, 0x3e38aa3b, v224
	v_fmamk_f32 v228, v73, 0x3e38aa3b, v224
	v_fmamk_f32 v229, v74, 0x3e38aa3b, v224
	v_fmamk_f32 v230, v75, 0x3e38aa3b, v224
	v_fmamk_f32 v231, v76, 0x3e38aa3b, v224
	v_fmamk_f32 v232, v77, 0x3e38aa3b, v224
	v_fmamk_f32 v225, v78, 0x3e38aa3b, v224
	v_fmamk_f32 v238, v79, 0x3e38aa3b, v224
	v_fmamk_f32 v239, v80, 0x3e38aa3b, v224
	v_fmac_f32_e32 v224, 0x3e38aa3b, v81
	s_waitcnt lgkmcnt(0)
	s_barrier
	ds_write_b128 v212, v[114:117]
	ds_write_b128 v213, v[118:121]
	ds_read_b128 v[66:69], v215 offset:32768
	ds_read_b128 v[70:73], v215 offset:36864
	v_exp_f32_e32 v164, v233
	v_exp_f32_e32 v233, v224
	v_add_f32_e32 v224, v153, v138
	s_waitcnt lgkmcnt(1)
	v_mfma_f32_32x32x16_bf16 v[82:97], v[66:69], v[110:113], 0
	v_add_f32_e32 v224, v139, v224
	v_add_f32_e32 v224, v152, v224
	v_add_f32_e32 v224, v140, v224
	ds_read_b128 v[240:243], v216 offset:32768
	ds_read_b128 v[244:247], v216 offset:36864
	v_add_f32_e32 v224, v151, v224
	v_add_f32_e32 v224, v141, v224
	v_add_f32_e32 v224, v150, v224
	s_waitcnt lgkmcnt(2)
	v_mfma_f32_32x32x16_bf16 v[66:81], v[70:73], v[110:113], 0
	v_add_f32_e32 v224, v142, v224
	v_add_f32_e32 v224, v149, v224
	v_add_f32_e32 v224, v143, v224
	v_add_f32_e32 v224, v148, v224
	v_add_f32_e32 v224, v144, v224
	v_exp_f32_e32 v165, v234
	v_add_f32_e32 v224, v147, v224
	s_waitcnt lgkmcnt(1)
	v_mfma_f32_32x32x16_bf16 v[82:97], v[240:243], v[106:109], v[82:97]
	v_exp_f32_e32 v166, v235
	v_add_f32_e32 v224, v145, v224
	v_exp_f32_e32 v167, v236
	v_add_f32_e32 v224, v146, v224
	v_exp_f32_e32 v172, v237
	v_add_f32_e32 v224, v164, v224
	v_exp_f32_e32 v173, v226
	s_waitcnt lgkmcnt(0)
	v_mfma_f32_32x32x16_bf16 v[66:81], v[244:247], v[106:109], v[66:81]
	ds_read_b128 v[240:243], v217 offset:32768
	ds_read_b128 v[244:247], v217 offset:36864
	v_add_f32_e32 v224, v165, v224
	v_exp_f32_e32 v174, v227
	v_add_f32_e32 v224, v166, v224
	v_exp_f32_e32 v175, v228
	v_add_f32_e32 v224, v167, v224
	v_exp_f32_e32 v226, v229
	s_waitcnt lgkmcnt(1)
	v_mfma_f32_32x32x16_bf16 v[82:97], v[240:243], v[102:105], v[82:97]
	v_add_f32_e32 v224, v172, v224
	v_exp_f32_e32 v227, v230
	v_add_f32_e32 v224, v173, v224
	v_exp_f32_e32 v228, v231
	v_add_f32_e32 v224, v174, v224
	v_exp_f32_e32 v229, v232
	v_add_f32_e32 v224, v175, v224
	s_waitcnt lgkmcnt(0)
	v_mfma_f32_32x32x16_bf16 v[66:81], v[244:247], v[102:105], v[66:81]
	ds_read_b128 v[240:243], v218 offset:32768
	ds_read_b128 v[244:247], v218 offset:36864
	v_exp_f32_e32 v230, v225
	v_add_f32_e32 v224, v226, v224
	v_exp_f32_e32 v231, v238
	v_add_f32_e32 v224, v227, v224
	v_exp_f32_e32 v232, v239
	v_add_f32_e32 v224, v228, v224
	s_waitcnt lgkmcnt(1)
	v_mfma_f32_32x32x16_bf16 v[82:97], v[240:243], v[98:101], v[82:97]
	v_add_f32_e32 v224, v229, v224
	v_add_f32_e32 v224, v230, v224
	v_add_f32_e32 v224, v231, v224
	v_add_f32_e32 v224, v232, v224
	v_add_f32_e32 v224, v233, v224
	v_mov_b32_e32 v225, v224
	v_cvt_pk_bf16_f32 v138, v138, v153
	s_waitcnt lgkmcnt(0)
	v_mfma_f32_32x32x16_bf16 v[66:81], v[244:247], v[98:101], v[66:81]
	v_cvt_pk_bf16_f32 v139, v139, v152
	v_cvt_pk_bf16_f32 v140, v140, v151
	v_cvt_pk_bf16_f32 v141, v141, v150
	v_cvt_pk_bf16_f32 v142, v142, v149
	v_cvt_pk_bf16_f32 v143, v143, v148
	v_cvt_pk_bf16_f32 v144, v144, v147
	v_cvt_pk_bf16_f32 v145, v145, v146
	v_cvt_pk_bf16_f32 v146, v164, v165
	v_cvt_pk_bf16_f32 v147, v166, v167
	v_cvt_pk_bf16_f32 v148, v172, v173
	v_cvt_pk_bf16_f32 v149, v174, v175
	v_cvt_pk_bf16_f32 v150, v226, v227
	v_cvt_pk_bf16_f32 v151, v228, v229
	v_cvt_pk_bf16_f32 v152, v230, v231
	v_cvt_pk_bf16_f32 v153, v232, v233
	v_permlane32_swap_b32_e32 v224, v225
	s_cmp_gt_u32 s8, 60
	s_cselect_b64 s[4:5], -1, 0
	s_and_b64 vcc, exec, s[4:5]
	s_cbranch_vccnz .Lod_d2
	global_load_dwordx4 v[114:117], v[178:179], off offset:2048
	global_load_dwordx4 v[118:121], v[180:181], off offset:2048
	global_load_dwordx4 v[122:125], v[204:205], off offset:1152
	s_mov_b32 s6, 0xa0000
	s_mov_b32 s7, 0
	s_nop 0
	v_lshl_add_u64 v[178:179], v[178:179], 0, s[6:7]
	v_lshl_add_u64 v[180:181], v[180:181], 0, s[6:7]
	v_lshl_add_u64 v[204:205], v[204:205], 0, s[6:7]

; #define SBAR() __builtin_amdgcn_sched_barrier(0)
; #define HOOK(P0, P1, j) do { if (NA) na_hook(P0, P1, krow0 + (j), q_row, q_col, win_r, win_c, rpb, inv_scale, hi); } while (0)
; __device__ __forceinline__ void finishSM(f32x16& p0, f32x16& p1, float alpha, float& l_reg, bf16x8& pa0, bf16x8& pa1, bf16x8& pa2, bf16x8& pa3) {
; #pragma unroll
;   for (int r = 0; r < 16; ++r) p1[r] = __builtin_amdgcn_exp2f(p1[r]);
;   float ps = 0;
; #pragma unroll
;   for (int r = 0; r < 16; ++r) ps += p0[r];
; #pragma unroll
;   for (int r = 0; r < 16; ++r) ps += p1[r];
;   { auto rr = __builtin_amdgcn_permlane32_swap(__float_as_uint(ps), __float_as_uint(ps), false, false);
;     ps = __uint_as_float(rr[0]) + __uint_as_float(rr[1]); }
;   l_reg = l_reg * alpha + ps;
;     ...
;   PK4(p0, 0, pa0); PK4(p0, 8, pa1); PK4(p1, 0, pa2); PK4(p1, 8, pa3);
; template <int DK, bool NA, bool QL, int SD> ...
;     ...
;   SBAR(); qkt<DK, QL>(pB0, pB1, (bf16*)((char*)K_lds + SHM_K), qr, ql, r32, hi); HOOK(pB0, pB1, NT - 1);
;   finishSM(pA0, pA1, alA, l_reg, pa0, pa1, pa2, pa3); SBAR();
;   pv_d0(o, vb0, pa0, pa1, pa2, pa3); partialSM(pB0, pB1, m_reg, mnB, alB, C, thrRaw);
.LBB0_713:
	ds_write_b128 v212, v[182:185] offset:16384
	ds_write_b128 v213, v[194:197] offset:16384
	ds_read_b128 v[66:69], v215 offset:49152
	ds_read_b128 v[70:73], v215 offset:53248
	v_exp_f32_e32 v118, v140
	v_exp_f32_e32 v119, v141
	v_exp_f32_e32 v120, v134
	s_waitcnt lgkmcnt(1)
	v_mfma_f32_32x32x16_bf16 v[82:97], v[66:69], v[110:113], 0
	v_exp_f32_e32 v121, v135
	v_exp_f32_e32 v122, v132
	v_exp_f32_e32 v123, v133
	s_waitcnt lgkmcnt(0)
	v_mfma_f32_32x32x16_bf16 v[66:81], v[70:73], v[110:113], 0
	ds_read_b128 v[110:113], v216 offset:49152
	ds_read_b128 v[114:117], v216 offset:53248
	s_waitcnt lgkmcnt(1)
	v_mfma_f32_32x32x16_bf16 v[82:97], v[110:113], v[106:109], v[82:97]
	s_waitcnt lgkmcnt(0)
	v_mfma_f32_32x32x16_bf16 v[66:81], v[114:117], v[106:109], v[66:81]
	ds_read_b128 v[106:109], v217 offset:49152
	ds_read_b128 v[110:113], v217 offset:53248
	v_exp_f32_e32 v114, v128
	v_exp_f32_e32 v115, v129
	v_exp_f32_e32 v116, v126
	v_exp_f32_e32 v117, v127
	s_waitcnt lgkmcnt(1)
	v_mfma_f32_32x32x16_bf16 v[82:97], v[106:109], v[102:105], v[82:97]
	s_waitcnt lgkmcnt(0)
	v_mfma_f32_32x32x16_bf16 v[66:81], v[110:113], v[102:105], v[66:81]
	ds_read_b128 v[102:105], v218 offset:49152
	ds_read_b128 v[106:109], v218 offset:53248
	v_exp_f32_e32 v110, v136
	v_exp_f32_e32 v111, v137
	v_exp_f32_e32 v112, v130
	v_exp_f32_e32 v113, v131
	s_waitcnt lgkmcnt(1)
	v_mfma_f32_32x32x16_bf16 v[82:97], v[102:105], v[98:101], v[82:97]
	s_waitcnt lgkmcnt(0)
	v_mfma_f32_32x32x16_bf16 v[66:81], v[106:109], v[98:101], v[66:81]
	v_add_f32_e32 v98, 0, v177
	v_add_f32_e32 v98, v226, v98
	v_add_f32_e32 v98, v161, v98
	v_add_f32_e32 v98, v223, v98
	v_add_f32_e32 v98, v153, v98
	v_add_f32_e32 v98, v176, v98
	v_add_f32_e32 v98, v152, v98
	v_add_f32_e32 v98, v160, v98
	v_add_f32_e32 v98, v149, v98
	v_add_f32_e32 v98, v151, v98
	v_add_f32_e32 v98, v147, v98
	v_add_f32_e32 v98, v150, v98
	v_exp_f32_e32 v108, v138
	v_add_f32_e32 v98, v145, v98
	v_exp_f32_e32 v109, v139
	v_add_f32_e32 v98, v148, v98
	v_add_f32_e32 v98, v144, v98
	v_add_f32_e32 v98, v146, v98
	v_add_f32_e32 v98, v108, v98
	v_add_f32_e32 v98, v109, v98
	v_add_f32_e32 v98, v110, v98
	v_add_f32_e32 v98, v111, v98
	v_add_f32_e32 v98, v112, v98
	v_add_f32_e32 v98, v113, v98
	v_add_f32_e32 v98, v114, v98
	v_add_f32_e32 v98, v115, v98
	v_add_f32_e32 v98, v116, v98
	v_add_f32_e32 v98, v117, v98
	v_add_f32_e32 v98, v118, v98
	v_add_f32_e32 v98, v119, v98
	v_add_f32_e32 v98, v120, v98
	v_add_f32_e32 v98, v121, v98
	v_add_f32_e32 v98, v122, v98
	v_add_f32_e32 v98, v123, v98
	v_mov_b32_e32 v99, v98
	v_cvt_pk_bf16_f32 v100, v177, v226
	v_cvt_pk_bf16_f32 v101, v161, v223
	v_cvt_pk_bf16_f32 v102, v153, v176
	v_cvt_pk_bf16_f32 v103, v152, v160
	s_nop 1
	v_permlane32_swap_b32_e32 v98, v99
	v_cvt_pk_bf16_f32 v104, v149, v151
	v_cvt_pk_bf16_f32 v105, v147, v150
	v_cvt_pk_bf16_f32 v106, v145, v148
	v_cvt_pk_bf16_f32 v107, v144, v146
	v_cvt_pk_bf16_f32 v108, v108, v109
	v_cvt_pk_bf16_f32 v109, v110, v111
	v_cvt_pk_bf16_f32 v110, v112, v113
	v_cvt_pk_bf16_f32 v111, v114, v115
	v_cvt_pk_bf16_f32 v112, v116, v117
	v_cvt_pk_bf16_f32 v113, v118, v119
	v_cvt_pk_bf16_f32 v114, v120, v121
	v_cvt_pk_bf16_f32 v115, v122, v123
	s_nop 0
	ds_read_b64_tr_b16 v[116:117], v211 offset:0
	ds_read_b64_tr_b16 v[118:119], v211 offset:0x800
	ds_read_b64_tr_b16 v[120:121], v211 offset:0x1000
	ds_read_b64_tr_b16 v[122:123], v211 offset:0x1800
	ds_read_b64_tr_b16 v[124:125], v211 offset:0x2000
	ds_read_b64_tr_b16 v[126:127], v211 offset:0x2800
	ds_read_b64_tr_b16 v[128:129], v211 offset:0x3000
	ds_read_b64_tr_b16 v[130:131], v211 offset:0x3800
	s_waitcnt lgkmcnt(0)
	s_nop 0
	v_mfma_f32_32x32x16_bf16 v[2:17], v[100:103], v[116:119], v[2:17]
	ds_read_b64_tr_b16 v[116:117], v211 offset:0x200
	ds_read_b64_tr_b16 v[118:119], v211 offset:0xa00
	v_mfma_f32_32x32x16_bf16 v[2:17], v[104:107], v[120:123], v[2:17]
	ds_read_b64_tr_b16 v[120:121], v211 offset:0x1200
	ds_read_b64_tr_b16 v[122:123], v211 offset:0x1a00
	v_mfma_f32_32x32x16_bf16 v[2:17], v[108:111], v[124:127], v[2:17]
	ds_read_b64_tr_b16 v[124:125], v211 offset:0x2200
	ds_read_b64_tr_b16 v[126:127], v211 offset:0x2a00
	v_mfma_f32_32x32x16_bf16 v[2:17], v[112:115], v[128:131], v[2:17]
	ds_read_b64_tr_b16 v[128:129], v211 offset:0x3200
	ds_read_b64_tr_b16 v[130:131], v211 offset:0x3a00
	s_waitcnt lgkmcnt(0)
	v_mfma_f32_32x32x16_bf16 v[50:65], v[100:103], v[116:119], v[50:65]
	ds_read_b64_tr_b16 v[116:117], v211 offset:0x400
	ds_read_b64_tr_b16 v[118:119], v211 offset:0xc00
	v_mfma_f32_32x32x16_bf16 v[50:65], v[104:107], v[120:123], v[50:65]
	ds_read_b64_tr_b16 v[120:121], v211 offset:0x1400
	ds_read_b64_tr_b16 v[122:123], v211 offset:0x1c00
	v_mfma_f32_32x32x16_bf16 v[50:65], v[108:111], v[124:127], v[50:65]
	ds_read_b64_tr_b16 v[124:125], v211 offset:0x2400
	ds_read_b64_tr_b16 v[126:127], v211 offset:0x2c00
	v_mfma_f32_32x32x16_bf16 v[50:65], v[112:115], v[128:131], v[50:65]
	ds_read_b64_tr_b16 v[128:129], v211 offset:0x3400
	ds_read_b64_tr_b16 v[130:131], v211 offset:0x3c00
	s_waitcnt lgkmcnt(0)
	v_mfma_f32_32x32x16_bf16 v[34:49], v[100:103], v[116:119], v[34:49]
	ds_read_b64_tr_b16 v[116:117], v211 offset:0x600
	ds_read_b64_tr_b16 v[118:119], v211 offset:0xe00
	v_mfma_f32_32x32x16_bf16 v[34:49], v[104:107], v[120:123], v[34:49]
	ds_read_b64_tr_b16 v[120:121], v211 offset:0x1600
	ds_read_b64_tr_b16 v[122:123], v211 offset:0x1e00
	v_mfma_f32_32x32x16_bf16 v[34:49], v[108:111], v[124:127], v[34:49]
	ds_read_b64_tr_b16 v[124:125], v211 offset:0x2600
	ds_read_b64_tr_b16 v[126:127], v211 offset:0x2e00
	v_mfma_f32_32x32x16_bf16 v[34:49], v[112:115], v[128:131], v[34:49]
	ds_read_b64_tr_b16 v[128:129], v211 offset:0x3600
	ds_read_b64_tr_b16 v[130:131], v211 offset:0x3e00
	s_waitcnt lgkmcnt(0)
; #define RESC(a) do { if (__any((a) < 1.f)) { if (hi == 0) al_l[r32] = (a); asm volatile("s_waitcnt lgkmcnt(0)" ::: "memory"); \
;     _Pragma("unroll") for (int d = 0; d < 4; ++d) _Pragma("unroll") for (int r = 0; r < 16; ++r) o[d][r] *= al_l[crow(r, hi)]; } } while (0)
; __device__ __forceinline__ void partialSM(f32x16& p0, f32x16& p1, float& m_reg, float& mn, float& alpha, float C, float thrRaw) {
;   float pmax = p0[0];
; #pragma unroll
;   for (int r = 1; r < 16; ++r) pmax = fmaxf(pmax, p0[r]);
; #pragma unroll
;   for (int r = 0; r < 16; ++r) pmax = fmaxf(pmax, p1[r]);
;   { auto rr = __builtin_amdgcn_permlane32_swap(__float_as_uint(pmax), __float_as_uint(pmax), false, false);
;     pmax = fmaxf(__uint_as_float(rr[0]), __uint_as_float(rr[1])); }
;   if (__builtin_expect(__all(pmax - m_reg <= thrRaw), 1)) { mn = m_reg; alpha = 1.f; }
;   else { mn = fmaxf(m_reg, pmax); alpha = __builtin_amdgcn_exp2f((m_reg - mn) * C); m_reg = mn; }
; template <int DK, bool NA, bool QL, int SD> ...
;     ...
;   pv_d0(o, vb0, pa0, pa1, pa2, pa3); partialSM(pB0, pB1, m_reg, mnB, alB, C, thrRaw);
;   __syncthreads(); RESC(alB);
	v_mfma_f32_32x32x16_bf16 v[18:33], v[100:103], v[116:119], v[18:33]
	v_max_f32_e32 v100, v83, v83
	v_max_f32_e32 v101, v82, v82
	v_max_f32_e32 v100, v101, v100
	v_max3_f32 v100, v100, v84, v85
	v_max3_f32 v100, v100, v86, v87
	v_max3_f32 v100, v100, v88, v89
	v_max3_f32 v100, v100, v90, v91
	v_max3_f32 v100, v100, v92, v93
	v_max3_f32 v100, v100, v94, v95
	v_mfma_f32_32x32x16_bf16 v[18:33], v[104:107], v[120:123], v[18:33]
	v_max3_f32 v100, v100, v96, v97
	v_max3_f32 v100, v100, v66, v67
	v_max3_f32 v100, v100, v68, v69
	v_max3_f32 v100, v100, v70, v71
	v_max3_f32 v100, v100, v72, v73
	v_max3_f32 v100, v100, v74, v75
	v_max3_f32 v100, v100, v76, v77
	v_max3_f32 v100, v100, v78, v79
	v_mfma_f32_32x32x16_bf16 v[18:33], v[108:111], v[124:127], v[18:33]
	v_max3_f32 v100, v100, v80, v81
	v_mov_b32_e32 v101, v100
	s_nop 1
	v_permlane32_swap_b32_e32 v100, v101
	v_max_f32_e32 v101, v101, v101
	v_max_f32_e32 v100, v100, v100
	v_max_f32_e32 v100, v100, v101
	v_sub_f32_e32 v101, v100, v142
	s_mov_b32 s2, 0x42800000
	v_cmp_ge_f32_e32 vcc, s2, v101
	v_max_f32_e32 v101, v142, v142
	v_max_f32_e32 v101, v101, v100
	v_mfma_f32_32x32x16_bf16 v[18:33], v[112:115], v[128:131], v[18:33]
	v_sub_f32_e32 v100, v142, v101
	v_mul_f32_e32 v100, 0x3e38aa3b, v100
	v_exp_f32_e32 v100, v100
	s_cmp_eq_u64 vcc, exec
	s_cselect_b64 s[2:3], -1, 0
	v_cndmask_b32_e64 v100, v100, 1.0, s[2:3]
	v_cmp_gt_f32_e32 vcc, 1.0, v100
	s_barrier
	s_cbranch_vccz .LBB0_717
	s_and_saveexec_b64 s[4:5], s[0:1]
	ds_write_b32 v208, v100 offset:128
	s_or_b64 exec, exec, s[4:5]
	s_waitcnt lgkmcnt(0)
	v_add_u32_e32 v114, v207, v0
	ds_read_b128 v[102:105], v114 offset:224
	ds_read_b128 v[106:109], v114 offset:192
	ds_read_b128 v[110:113], v114 offset:160
	ds_read_b128 v[114:117], v114 offset:128
	s_waitcnt lgkmcnt(3)
	v_pk_mul_f32 v[14:15], v[14:15], v[102:103]
	s_waitcnt lgkmcnt(2)
	v_pk_mul_f32 v[10:11], v[10:11], v[106:107]
	s_waitcnt lgkmcnt(1)
	v_pk_mul_f32 v[6:7], v[6:7], v[110:111]
	v_pk_mul_f32 v[16:17], v[16:17], v[104:105]
	v_pk_mul_f32 v[12:13], v[12:13], v[108:109]
	v_pk_mul_f32 v[8:9], v[8:9], v[112:113]
	s_waitcnt lgkmcnt(0)
	v_pk_mul_f32 v[4:5], v[4:5], v[116:117]
	v_pk_mul_f32 v[2:3], v[2:3], v[114:115]
	v_pk_mul_f32 v[62:63], v[102:103], v[62:63]
	v_pk_mul_f32 v[58:59], v[106:107], v[58:59]
	v_pk_mul_f32 v[54:55], v[110:111], v[54:55]
	v_pk_mul_f32 v[64:65], v[104:105], v[64:65]
	v_pk_mul_f32 v[60:61], v[108:109], v[60:61]
	v_pk_mul_f32 v[56:57], v[112:113], v[56:57]
	v_pk_mul_f32 v[52:53], v[116:117], v[52:53]
	v_pk_mul_f32 v[50:51], v[114:115], v[50:51]
	v_pk_mul_f32 v[46:47], v[102:103], v[46:47]
	v_pk_mul_f32 v[42:43], v[106:107], v[42:43]
	v_pk_mul_f32 v[38:39], v[110:111], v[38:39]
	v_pk_mul_f32 v[48:49], v[104:105], v[48:49]
	v_pk_mul_f32 v[44:45], v[108:109], v[44:45]
	v_pk_mul_f32 v[40:41], v[112:113], v[40:41]
	v_pk_mul_f32 v[36:37], v[116:117], v[36:37]
	v_pk_mul_f32 v[34:35], v[114:115], v[34:35]
	v_pk_mul_f32 v[30:31], v[102:103], v[30:31]
	v_pk_mul_f32 v[26:27], v[106:107], v[26:27]
	v_pk_mul_f32 v[22:23], v[110:111], v[22:23]
	v_pk_mul_f32 v[32:33], v[104:105], v[32:33]
	v_pk_mul_f32 v[28:29], v[108:109], v[28:29]
	v_pk_mul_f32 v[24:25], v[112:113], v[24:25]
	v_pk_mul_f32 v[20:21], v[116:117], v[20:21]
	v_pk_mul_f32 v[18:19], v[114:115], v[18:19]
; #define SBAR() __builtin_amdgcn_sched_barrier(0)
; __device__ __forceinline__ void finishSM(f32x16& p0, f32x16& p1, float alpha, float& l_reg, bf16x8& pa0, bf16x8& pa1, bf16x8& pa2, bf16x8& pa3) {
; #pragma unroll
;   for (int r = 0; r < 16; ++r) p1[r] = __builtin_amdgcn_exp2f(p1[r]);
;   float ps = 0;
; #pragma unroll
;   for (int r = 0; r < 16; ++r) ps += p0[r];
; #pragma unroll
;   for (int r = 0; r < 16; ++r) ps += p1[r];
;   { auto rr = __builtin_amdgcn_permlane32_swap(__float_as_uint(ps), __float_as_uint(ps), false, false);
;     ps = __uint_as_float(rr[0]) + __uint_as_float(rr[1]); }
;   l_reg = l_reg * alpha + ps;
;     ...
;   PK4(p0, 0, pa0); PK4(p0, 8, pa1); PK4(p1, 0, pa2); PK4(p1, 8, pa3);
; template <int DK, bool NA, bool QL, int SD> ...
;     ...
;   finishSM(pB0, pB1, alB, l_reg, pa0, pa1, pa2, pa3); SBAR();
;   pv_d0(o, vb0 + (int)SHM_V, pa0, pa1, pa2, pa3);
;   if (hi == 0) li_l[r32] = l_reg; asm volatile("s_waitcnt vmcnt(0) lgkmcnt(0)" ::: "memory");
.LBB0_717:
	v_cndmask_b32_e64 v101, v101, v142, s[2:3]
	v_mul_f32_e32 v101, 0xbe38aa3b, v101
	v_fmamk_f32 v82, v82, 0x3e38aa3b, v101
	v_fmamk_f32 v83, v83, 0x3e38aa3b, v101
	v_fmamk_f32 v102, v84, 0x3e38aa3b, v101
	v_exp_f32_e32 v84, v82
	v_fmamk_f32 v103, v86, 0x3e38aa3b, v101
	v_exp_f32_e32 v86, v83
	v_fmamk_f32 v85, v85, 0x3e38aa3b, v101
	v_exp_f32_e32 v82, v102
	v_fmamk_f32 v66, v66, 0x3e38aa3b, v101
	v_exp_f32_e32 v85, v85
	v_fmamk_f32 v104, v87, 0x3e38aa3b, v101
	v_fmamk_f32 v113, v96, 0x3e38aa3b, v101
	v_fmamk_f32 v96, v77, 0x3e38aa3b, v101
	v_exp_f32_e32 v77, v103
	v_exp_f32_e32 v102, v66
	v_add_f32_e32 v66, 0, v84
	v_fmamk_f32 v105, v88, 0x3e38aa3b, v101
	v_exp_f32_e32 v83, v104
	v_add_f32_e32 v66, v86, v66
	v_fmamk_f32 v106, v89, 0x3e38aa3b, v101
	v_fmamk_f32 v112, v95, 0x3e38aa3b, v101
	v_fmamk_f32 v95, v76, 0x3e38aa3b, v101
	v_exp_f32_e32 v76, v105
	v_add_f32_e32 v66, v82, v66
	v_fmamk_f32 v107, v90, 0x3e38aa3b, v101
	v_fmamk_f32 v114, v97, 0x3e38aa3b, v101
	v_fmamk_f32 v97, v78, 0x3e38aa3b, v101
	v_exp_f32_e32 v78, v106
	v_add_f32_e32 v66, v85, v66
	v_fmamk_f32 v108, v91, 0x3e38aa3b, v101
	v_fmamk_f32 v109, v92, 0x3e38aa3b, v101
	v_fmamk_f32 v92, v73, 0x3e38aa3b, v101
	v_exp_f32_e32 v73, v107
	v_add_f32_e32 v66, v77, v66
	v_fmamk_f32 v111, v94, 0x3e38aa3b, v101
	v_fmamk_f32 v94, v75, 0x3e38aa3b, v101
	v_exp_f32_e32 v75, v108
	v_add_f32_e32 v66, v83, v66
	v_fmamk_f32 v110, v93, 0x3e38aa3b, v101
	v_fmamk_f32 v90, v71, 0x3e38aa3b, v101
	v_exp_f32_e32 v71, v109
	v_add_f32_e32 v66, v76, v66
	v_fmamk_f32 v93, v74, 0x3e38aa3b, v101
	v_exp_f32_e32 v74, v110
	v_add_f32_e32 v66, v78, v66
	v_fmamk_f32 v88, v69, 0x3e38aa3b, v101
	v_exp_f32_e32 v69, v111
	v_add_f32_e32 v66, v73, v66
	v_fmamk_f32 v91, v72, 0x3e38aa3b, v101
	v_exp_f32_e32 v72, v112
	v_add_f32_e32 v66, v75, v66
	v_fmamk_f32 v87, v68, 0x3e38aa3b, v101
	v_exp_f32_e32 v68, v113
	v_add_f32_e32 v66, v71, v66
	v_fmamk_f32 v89, v70, 0x3e38aa3b, v101
	v_exp_f32_e32 v70, v114
	v_add_f32_e32 v66, v74, v66
	v_fmamk_f32 v67, v67, 0x3e38aa3b, v101
	v_add_f32_e32 v66, v69, v66
	v_exp_f32_e32 v103, v67
	v_add_f32_e32 v66, v72, v66
	v_exp_f32_e32 v87, v87
	v_add_f32_e32 v66, v68, v66
	v_exp_f32_e32 v88, v88
	v_add_f32_e32 v66, v70, v66
	v_exp_f32_e32 v89, v89
	v_add_f32_e32 v66, v102, v66
	v_exp_f32_e32 v90, v90
	v_add_f32_e32 v66, v103, v66
	v_exp_f32_e32 v91, v91
	v_add_f32_e32 v66, v87, v66
	v_exp_f32_e32 v92, v92
	v_add_f32_e32 v66, v88, v66
	v_exp_f32_e32 v93, v93
	v_add_f32_e32 v66, v89, v66
	v_exp_f32_e32 v94, v94
	v_add_f32_e32 v66, v90, v66
	v_exp_f32_e32 v95, v95
	v_add_f32_e32 v66, v91, v66
	v_exp_f32_e32 v96, v96
	v_add_f32_e32 v66, v92, v66
	v_fmamk_f32 v79, v79, 0x3e38aa3b, v101
	v_exp_f32_e32 v97, v97
	v_add_f32_e32 v66, v93, v66
	v_fmamk_f32 v80, v80, 0x3e38aa3b, v101
	v_exp_f32_e32 v104, v79
	v_add_f32_e32 v66, v94, v66
	v_fmac_f32_e32 v101, 0x3e38aa3b, v81
	v_exp_f32_e32 v105, v80
	v_add_f32_e32 v66, v95, v66
	v_exp_f32_e32 v101, v101
	v_add_f32_e32 v66, v96, v66
	v_add_f32_e32 v66, v97, v66
	v_add_f32_e32 v66, v104, v66
	v_add_f32_e32 v66, v105, v66
	v_add_f32_e32 v66, v101, v66
	v_mov_b32_e32 v67, v66
	s_nop 1
	v_permlane32_swap_b32_e32 v66, v67
	v_cvt_pk_bf16_f32 v80, v84, v86
	v_cvt_pk_bf16_f32 v81, v82, v85
	v_cvt_pk_bf16_f32 v82, v77, v83
	v_cvt_pk_bf16_f32 v83, v76, v78
	v_cvt_pk_bf16_f32 v76, v73, v75
	v_cvt_pk_bf16_f32 v77, v71, v74
	v_cvt_pk_bf16_f32 v78, v69, v72
	v_cvt_pk_bf16_f32 v79, v68, v70
	v_cvt_pk_bf16_f32 v68, v102, v103
	v_cvt_pk_bf16_f32 v69, v87, v88
	v_cvt_pk_bf16_f32 v70, v89, v90
	v_cvt_pk_bf16_f32 v71, v91, v92
	v_cvt_pk_bf16_f32 v72, v93, v94
	v_cvt_pk_bf16_f32 v73, v95, v96
	v_cvt_pk_bf16_f32 v74, v97, v104
	v_cvt_pk_bf16_f32 v75, v105, v101
	s_nop 0
	ds_read_b64_tr_b16 v[84:85], v210 offset:0
	ds_read_b64_tr_b16 v[86:87], v210 offset:0x800
	ds_read_b64_tr_b16 v[88:89], v210 offset:0x1000
	ds_read_b64_tr_b16 v[90:91], v210 offset:0x1800
	ds_read_b64_tr_b16 v[92:93], v210 offset:0x2000
	ds_read_b64_tr_b16 v[94:95], v210 offset:0x2800
	ds_read_b64_tr_b16 v[102:103], v210 offset:0x3000
	ds_read_b64_tr_b16 v[104:105], v210 offset:0x3800
	s_waitcnt lgkmcnt(0)
	s_nop 0
	v_mfma_f32_32x32x16_bf16 v[2:17], v[80:83], v[84:87], v[2:17]
	ds_read_b64_tr_b16 v[84:85], v210 offset:0x200
	ds_read_b64_tr_b16 v[86:87], v210 offset:0xa00
	v_mfma_f32_32x32x16_bf16 v[2:17], v[76:79], v[88:91], v[2:17]
	ds_read_b64_tr_b16 v[88:89], v210 offset:0x1200
	ds_read_b64_tr_b16 v[90:91], v210 offset:0x1a00
	v_mfma_f32_32x32x16_bf16 v[2:17], v[68:71], v[92:95], v[2:17]
	ds_read_b64_tr_b16 v[92:93], v210 offset:0x2200
	ds_read_b64_tr_b16 v[94:95], v210 offset:0x2a00
	v_mfma_f32_32x32x16_bf16 v[2:17], v[72:75], v[102:105], v[2:17]
	ds_read_b64_tr_b16 v[102:103], v210 offset:0x3200
	ds_read_b64_tr_b16 v[104:105], v210 offset:0x3a00
	s_waitcnt lgkmcnt(0)
	v_mfma_f32_32x32x16_bf16 v[50:65], v[80:83], v[84:87], v[50:65]
	ds_read_b64_tr_b16 v[84:85], v210 offset:0x400
	ds_read_b64_tr_b16 v[86:87], v210 offset:0xc00
	v_mfma_f32_32x32x16_bf16 v[50:65], v[76:79], v[88:91], v[50:65]
	ds_read_b64_tr_b16 v[88:89], v210 offset:0x1400
	ds_read_b64_tr_b16 v[90:91], v210 offset:0x1c00
	v_mfma_f32_32x32x16_bf16 v[50:65], v[68:71], v[92:95], v[50:65]
	ds_read_b64_tr_b16 v[92:93], v210 offset:0x2400
	ds_read_b64_tr_b16 v[94:95], v210 offset:0x2c00
	v_mfma_f32_32x32x16_bf16 v[50:65], v[72:75], v[102:105], v[50:65]
	ds_read_b64_tr_b16 v[102:103], v210 offset:0x3400
	ds_read_b64_tr_b16 v[104:105], v210 offset:0x3c00
	s_waitcnt lgkmcnt(0)
	v_mfma_f32_32x32x16_bf16 v[34:49], v[80:83], v[84:87], v[34:49]
	ds_read_b64_tr_b16 v[84:85], v210 offset:0x600
	ds_read_b64_tr_b16 v[86:87], v210 offset:0xe00
	v_mfma_f32_32x32x16_bf16 v[34:49], v[76:79], v[88:91], v[34:49]
	ds_read_b64_tr_b16 v[88:89], v210 offset:0x1600
	ds_read_b64_tr_b16 v[90:91], v210 offset:0x1e00
	v_mfma_f32_32x32x16_bf16 v[34:49], v[68:71], v[92:95], v[34:49]
	ds_read_b64_tr_b16 v[92:93], v210 offset:0x2600
	ds_read_b64_tr_b16 v[94:95], v210 offset:0x2e00
	v_mfma_f32_32x32x16_bf16 v[34:49], v[72:75], v[102:105], v[34:49]
	ds_read_b64_tr_b16 v[102:103], v210 offset:0x3600
	ds_read_b64_tr_b16 v[104:105], v210 offset:0x3e00
	s_waitcnt lgkmcnt(0)
	v_mfma_f32_32x32x16_bf16 v[18:33], v[80:83], v[84:87], v[18:33]
	v_mfma_f32_32x32x16_bf16 v[18:33], v[76:79], v[88:91], v[18:33]
	v_mfma_f32_32x32x16_bf16 v[18:33], v[68:71], v[92:95], v[18:33]
	v_mfma_f32_32x32x16_bf16 v[18:33], v[72:75], v[102:105], v[18:33]
	s_and_saveexec_b64 s[2:3], s[0:1]
	s_cbranch_execz .LBB0_368
	v_add_f32_e32 v68, v98, v99
	v_fmac_f32_e32 v68, v209, v143
	v_add_f32_e32 v66, v66, v67
	v_fmac_f32_e32 v66, v68, v100
	ds_write_b32 v208, v66
	s_branch .LBB0_368
